# v_d1 + serpentine MFMA order in GEMM K-loop blocks (operand register reuse between consecutive MFMAs)
# speedup vs baseline: 1.0046x; 1.0046x over previous
.LBB0_524:
	ds_read_b128 v[132:135], v147
	ds_read_b128 v[136:139], v147 offset:1024
	ds_read_b128 v[152:155], v147 offset:2048
	ds_read_b128 v[156:159], v147 offset:3072
	ds_read_b128 v[160:163], v148
	ds_read_b128 v[164:167], v148 offset:1024
	ds_read_b128 v[168:171], v148 offset:2048
	ds_read_b128 v[172:175], v148 offset:3072
	s_add_u32 s26, s36, 0x100
	s_addc_u32 s27, s37, 0
	s_cmp_eq_u32 s87, 12
	s_cselect_b32 s42, s19, s26
	s_cselect_b32 s43, s17, s27
	s_cselect_b32 s38, s84, s85
	s_cselect_b32 s39, s83, s86
	s_add_u32 s34, s42, 0x80
	s_addc_u32 s35, s43, 0
	ds_read_b128 v[176:179], v149
	ds_read_b128 v[180:183], v149 offset:1024
	ds_read_b128 v[186:189], v149 offset:2048
	ds_read_b128 v[190:193], v149 offset:3072
	ds_read_b128 v[194:197], v149 offset:4096
	ds_read_b128 v[198:201], v149 offset:5120
	ds_read_b128 v[202:205], v149 offset:6144
	ds_read_b128 v[206:209], v149 offset:7168
	s_add_u32 s36, s36, 0x40080
	s_addc_u32 s37, s37, 0
	s_mov_b32 s58, m0
	s_mov_b32 m0, s62
	s_nop 0
	global_load_lds_dwordx4 v142, s[36:37]
	s_mov_b32 m0, s58
	s_nop 0
	s_mov_b32 s58, m0
	s_mov_b32 m0, s69
	s_nop 0
	global_load_lds_dwordx4 v143, s[36:37]
	s_mov_b32 m0, s58
	s_waitcnt vmcnt(8)
	s_waitcnt lgkmcnt(0)
	s_barrier
	s_setprio 1
	s_waitcnt lgkmcnt(7)
	v_mfma_f32_16x16x32_bf16 v[120:123], v[132:135], v[176:179], v[120:123]
	v_mfma_f32_16x16x32_bf16 v[112:115], v[152:155], v[176:179], v[112:115]
	s_waitcnt lgkmcnt(5)
	v_mfma_f32_16x16x32_bf16 v[96:99], v[152:155], v[186:189], v[96:99]
	v_mfma_f32_16x16x32_bf16 v[104:107], v[132:135], v[186:189], v[104:107]
	s_waitcnt lgkmcnt(3)
	v_mfma_f32_16x16x32_bf16 v[88:91], v[132:135], v[194:197], v[88:91]
	v_mfma_f32_16x16x32_bf16 v[80:83], v[152:155], v[194:197], v[80:83]
	s_waitcnt lgkmcnt(1)
	v_mfma_f32_16x16x32_bf16 v[56:59], v[152:155], v[202:205], v[56:59]
	v_mfma_f32_16x16x32_bf16 v[72:75], v[132:135], v[202:205], v[72:75]
	v_mfma_f32_16x16x32_bf16 v[120:123], v[136:139], v[180:183], v[120:123]
	v_mfma_f32_16x16x32_bf16 v[112:115], v[156:159], v[180:183], v[112:115]
	v_mfma_f32_16x16x32_bf16 v[96:99], v[156:159], v[190:193], v[96:99]
	v_mfma_f32_16x16x32_bf16 v[104:107], v[136:139], v[190:193], v[104:107]
	v_mfma_f32_16x16x32_bf16 v[88:91], v[136:139], v[198:201], v[88:91]
	v_mfma_f32_16x16x32_bf16 v[80:83], v[156:159], v[198:201], v[80:83]
	s_waitcnt lgkmcnt(0)
	v_mfma_f32_16x16x32_bf16 v[56:59], v[156:159], v[206:209], v[56:59]
	v_mfma_f32_16x16x32_bf16 v[72:75], v[136:139], v[206:209], v[72:75]
	s_setprio 0
	s_setprio 1
	v_mfma_f32_16x16x32_bf16 v[124:127], v[160:163], v[176:179], v[124:127]
	v_mfma_f32_16x16x32_bf16 v[116:119], v[168:171], v[176:179], v[116:119]
	v_mfma_f32_16x16x32_bf16 v[100:103], v[168:171], v[186:189], v[100:103]
	v_mfma_f32_16x16x32_bf16 v[108:111], v[160:163], v[186:189], v[108:111]
	v_mfma_f32_16x16x32_bf16 v[92:95], v[160:163], v[194:197], v[92:95]
	v_mfma_f32_16x16x32_bf16 v[84:87], v[168:171], v[194:197], v[84:87]
	v_mfma_f32_16x16x32_bf16 v[64:67], v[168:171], v[202:205], v[64:67]
	v_mfma_f32_16x16x32_bf16 v[76:79], v[160:163], v[202:205], v[76:79]
	v_mfma_f32_16x16x32_bf16 v[124:127], v[164:167], v[180:183], v[124:127]
	v_mfma_f32_16x16x32_bf16 v[116:119], v[172:175], v[180:183], v[116:119]
	v_mfma_f32_16x16x32_bf16 v[100:103], v[172:175], v[190:193], v[100:103]
	v_mfma_f32_16x16x32_bf16 v[108:111], v[164:167], v[190:193], v[108:111]
	v_mfma_f32_16x16x32_bf16 v[92:95], v[164:167], v[198:201], v[92:95]
	v_mfma_f32_16x16x32_bf16 v[84:87], v[172:175], v[198:201], v[84:87]
	v_mfma_f32_16x16x32_bf16 v[64:67], v[172:175], v[206:209], v[64:67]
	v_mfma_f32_16x16x32_bf16 v[76:79], v[164:167], v[206:209], v[76:79]
	s_setprio 0
	s_barrier
	ds_read_b128 v[176:179], v149 offset:16384
	ds_read_b128 v[180:183], v149 offset:17408
	ds_read_b128 v[186:189], v149 offset:18432
	ds_read_b128 v[190:193], v149 offset:19456
	ds_read_b128 v[194:197], v149 offset:20480
	ds_read_b128 v[198:201], v149 offset:21504
	ds_read_b128 v[202:205], v149 offset:22528
	ds_read_b128 v[206:209], v149 offset:23552
	s_mov_b32 s36, m0
	s_mov_b32 m0, s63
	s_nop 0
	global_load_lds_dwordx4 v140, s[38:39]
	s_mov_b32 m0, s36
	s_nop 0
	s_mov_b32 s36, m0
	s_mov_b32 m0, s70
	s_nop 0
	global_load_lds_dwordx4 v141, s[38:39]
	s_mov_b32 m0, s36
	s_add_u32 s36, s38, 0x40000
	s_addc_u32 s37, s39, 0
	s_mov_b32 s58, m0
	s_mov_b32 m0, s68
	s_nop 0
	global_load_lds_dwordx4 v140, s[36:37]
	s_mov_b32 m0, s58
	s_nop 0
	s_mov_b32 s58, m0
	s_mov_b32 m0, s72
	s_nop 0
	global_load_lds_dwordx4 v141, s[36:37]
	s_mov_b32 m0, s58
	s_mov_b32 s36, m0
	s_mov_b32 m0, s25
	s_nop 0
	global_load_lds_dwordx4 v142, s[42:43]
	s_mov_b32 m0, s36
	s_nop 0
	s_mov_b32 s36, m0
	s_mov_b32 m0, s48
	s_nop 0
	global_load_lds_dwordx4 v143, s[42:43]
	s_mov_b32 m0, s36
	s_waitcnt vmcnt(8)
	s_waitcnt lgkmcnt(0)
	s_barrier
	s_setprio 1
	s_waitcnt lgkmcnt(7)
	v_mfma_f32_16x16x32_bf16 v[60:63], v[132:135], v[176:179], v[60:63]
	v_mfma_f32_16x16x32_bf16 v[48:51], v[152:155], v[176:179], v[48:51]
	s_waitcnt lgkmcnt(5)
	v_mfma_f32_16x16x32_bf16 v[32:35], v[152:155], v[186:189], v[32:35]
	v_mfma_f32_16x16x32_bf16 v[40:43], v[132:135], v[186:189], v[40:43]
	s_waitcnt lgkmcnt(3)
	v_mfma_f32_16x16x32_bf16 v[24:27], v[132:135], v[194:197], v[24:27]
	v_mfma_f32_16x16x32_bf16 v[16:19], v[152:155], v[194:197], v[16:19]
	s_waitcnt lgkmcnt(1)
	v_mfma_f32_16x16x32_bf16 v[0:3], v[152:155], v[202:205], v[0:3]
	v_mfma_f32_16x16x32_bf16 v[8:11], v[132:135], v[202:205], v[8:11]
	v_mfma_f32_16x16x32_bf16 v[60:63], v[136:139], v[180:183], v[60:63]
	v_mfma_f32_16x16x32_bf16 v[48:51], v[156:159], v[180:183], v[48:51]
	v_mfma_f32_16x16x32_bf16 v[32:35], v[156:159], v[190:193], v[32:35]
	v_mfma_f32_16x16x32_bf16 v[40:43], v[136:139], v[190:193], v[40:43]
	v_mfma_f32_16x16x32_bf16 v[24:27], v[136:139], v[198:201], v[24:27]
	v_mfma_f32_16x16x32_bf16 v[16:19], v[156:159], v[198:201], v[16:19]
	s_waitcnt lgkmcnt(0)
	v_mfma_f32_16x16x32_bf16 v[0:3], v[156:159], v[206:209], v[0:3]
	v_mfma_f32_16x16x32_bf16 v[8:11], v[136:139], v[206:209], v[8:11]
	s_setprio 0
	s_setprio 1
	v_mfma_f32_16x16x32_bf16 v[68:71], v[160:163], v[176:179], v[68:71]
	v_mfma_f32_16x16x32_bf16 v[52:55], v[168:171], v[176:179], v[52:55]
	v_mfma_f32_16x16x32_bf16 v[36:39], v[168:171], v[186:189], v[36:39]
	v_mfma_f32_16x16x32_bf16 v[44:47], v[160:163], v[186:189], v[44:47]
	v_mfma_f32_16x16x32_bf16 v[28:31], v[160:163], v[194:197], v[28:31]
	v_mfma_f32_16x16x32_bf16 v[20:23], v[168:171], v[194:197], v[20:23]
	v_mfma_f32_16x16x32_bf16 v[4:7], v[168:171], v[202:205], v[4:7]
	v_mfma_f32_16x16x32_bf16 v[12:15], v[160:163], v[202:205], v[12:15]
	v_mfma_f32_16x16x32_bf16 v[68:71], v[164:167], v[180:183], v[68:71]
	v_mfma_f32_16x16x32_bf16 v[52:55], v[172:175], v[180:183], v[52:55]
	v_mfma_f32_16x16x32_bf16 v[36:39], v[172:175], v[190:193], v[36:39]
	v_mfma_f32_16x16x32_bf16 v[44:47], v[164:167], v[190:193], v[44:47]
	v_mfma_f32_16x16x32_bf16 v[28:31], v[164:167], v[198:201], v[28:31]
	v_mfma_f32_16x16x32_bf16 v[20:23], v[172:175], v[198:201], v[20:23]
	v_mfma_f32_16x16x32_bf16 v[4:7], v[172:175], v[206:209], v[4:7]
	v_mfma_f32_16x16x32_bf16 v[12:15], v[164:167], v[206:209], v[12:15]
	s_setprio 0
	s_barrier
	ds_read_b128 v[132:135], v150
	ds_read_b128 v[136:139], v150 offset:1024
	ds_read_b128 v[152:155], v150 offset:2048
	ds_read_b128 v[156:159], v150 offset:3072
	ds_read_b128 v[160:163], v151
	ds_read_b128 v[164:167], v151 offset:1024
	ds_read_b128 v[168:171], v151 offset:2048
	ds_read_b128 v[172:175], v151 offset:3072
	ds_read_b128 v[176:179], v149 offset:32768
	ds_read_b128 v[180:183], v149 offset:33792
	ds_read_b128 v[186:189], v149 offset:34816
	ds_read_b128 v[190:193], v149 offset:35840
	ds_read_b128 v[194:197], v149 offset:36864
	ds_read_b128 v[198:201], v149 offset:37888
	ds_read_b128 v[202:205], v149 offset:38912
	ds_read_b128 v[206:209], v149 offset:39936
	s_add_u32 s36, s42, 0x40000
	s_addc_u32 s37, s43, 0
	s_mov_b32 s42, m0
	s_mov_b32 m0, s49
	s_nop 0
	global_load_lds_dwordx4 v142, s[36:37]
	s_mov_b32 m0, s42
	s_nop 0
	s_mov_b32 s42, m0
	s_mov_b32 m0, s50
	s_nop 0
	global_load_lds_dwordx4 v143, s[36:37]
	s_mov_b32 m0, s42
	s_waitcnt vmcnt(8)
	s_waitcnt lgkmcnt(0)
	s_barrier
	s_setprio 1
	s_waitcnt lgkmcnt(7)
	v_mfma_f32_16x16x32_bf16 v[120:123], v[132:135], v[176:179], v[120:123]
	v_mfma_f32_16x16x32_bf16 v[112:115], v[152:155], v[176:179], v[112:115]
	s_waitcnt lgkmcnt(5)
	v_mfma_f32_16x16x32_bf16 v[96:99], v[152:155], v[186:189], v[96:99]
	v_mfma_f32_16x16x32_bf16 v[104:107], v[132:135], v[186:189], v[104:107]
	s_waitcnt lgkmcnt(3)
	v_mfma_f32_16x16x32_bf16 v[88:91], v[132:135], v[194:197], v[88:91]
	v_mfma_f32_16x16x32_bf16 v[80:83], v[152:155], v[194:197], v[80:83]
	s_waitcnt lgkmcnt(1)
	v_mfma_f32_16x16x32_bf16 v[56:59], v[152:155], v[202:205], v[56:59]
	v_mfma_f32_16x16x32_bf16 v[72:75], v[132:135], v[202:205], v[72:75]
	v_mfma_f32_16x16x32_bf16 v[120:123], v[136:139], v[180:183], v[120:123]
	v_mfma_f32_16x16x32_bf16 v[112:115], v[156:159], v[180:183], v[112:115]
	v_mfma_f32_16x16x32_bf16 v[96:99], v[156:159], v[190:193], v[96:99]
	v_mfma_f32_16x16x32_bf16 v[104:107], v[136:139], v[190:193], v[104:107]
	v_mfma_f32_16x16x32_bf16 v[88:91], v[136:139], v[198:201], v[88:91]
	v_mfma_f32_16x16x32_bf16 v[80:83], v[156:159], v[198:201], v[80:83]
	s_waitcnt lgkmcnt(0)
	v_mfma_f32_16x16x32_bf16 v[56:59], v[156:159], v[206:209], v[56:59]
	v_mfma_f32_16x16x32_bf16 v[72:75], v[136:139], v[206:209], v[72:75]
	s_setprio 0
	s_setprio 1
	v_mfma_f32_16x16x32_bf16 v[124:127], v[160:163], v[176:179], v[124:127]
	v_mfma_f32_16x16x32_bf16 v[116:119], v[168:171], v[176:179], v[116:119]
	v_mfma_f32_16x16x32_bf16 v[100:103], v[168:171], v[186:189], v[100:103]
	v_mfma_f32_16x16x32_bf16 v[108:111], v[160:163], v[186:189], v[108:111]
	v_mfma_f32_16x16x32_bf16 v[92:95], v[160:163], v[194:197], v[92:95]
	v_mfma_f32_16x16x32_bf16 v[84:87], v[168:171], v[194:197], v[84:87]
	v_mfma_f32_16x16x32_bf16 v[64:67], v[168:171], v[202:205], v[64:67]
	v_mfma_f32_16x16x32_bf16 v[76:79], v[160:163], v[202:205], v[76:79]
	v_mfma_f32_16x16x32_bf16 v[124:127], v[164:167], v[180:183], v[124:127]
	v_mfma_f32_16x16x32_bf16 v[116:119], v[172:175], v[180:183], v[116:119]
	v_mfma_f32_16x16x32_bf16 v[100:103], v[172:175], v[190:193], v[100:103]
	v_mfma_f32_16x16x32_bf16 v[108:111], v[164:167], v[190:193], v[108:111]
	v_mfma_f32_16x16x32_bf16 v[92:95], v[164:167], v[198:201], v[92:95]
	v_mfma_f32_16x16x32_bf16 v[84:87], v[172:175], v[198:201], v[84:87]
	v_mfma_f32_16x16x32_bf16 v[64:67], v[172:175], v[206:209], v[64:67]
	v_mfma_f32_16x16x32_bf16 v[76:79], v[164:167], v[206:209], v[76:79]
	s_setprio 0
	s_barrier
	ds_read_b128 v[176:179], v149 offset:49152
	ds_read_b128 v[180:183], v149 offset:50176
	ds_read_b128 v[186:189], v149 offset:51200
	ds_read_b128 v[190:193], v149 offset:52224
	ds_read_b128 v[194:197], v149 offset:53248
	ds_read_b128 v[198:201], v149 offset:54272
	ds_read_b128 v[202:205], v149 offset:55296
	ds_read_b128 v[206:209], v149 offset:56320
	s_add_u32 s36, s38, 0x80
	s_addc_u32 s37, s39, 0
	s_mov_b32 s42, m0
	s_mov_b32 m0, s52
	s_nop 0
	global_load_lds_dwordx4 v140, s[36:37]
	s_mov_b32 m0, s42
	s_nop 0
	s_mov_b32 s42, m0
	s_mov_b32 m0, s53
	s_nop 0
	global_load_lds_dwordx4 v141, s[36:37]
	s_mov_b32 m0, s42
	s_add_u32 s36, s38, 0x40080
	s_addc_u32 s37, s39, 0
	s_mov_b32 s38, m0
	s_mov_b32 m0, s60
	s_nop 0
	global_load_lds_dwordx4 v140, s[36:37]
	s_mov_b32 m0, s38
	s_nop 0
	s_mov_b32 s38, m0
	s_mov_b32 m0, s61
	s_nop 0
	global_load_lds_dwordx4 v141, s[36:37]
	s_mov_b32 m0, s38
	s_mov_b32 s36, m0
	s_mov_b32 m0, s54
	s_nop 0
	global_load_lds_dwordx4 v142, s[34:35]
	s_mov_b32 m0, s36
	s_nop 0
	s_mov_b32 s36, m0
	s_mov_b32 m0, s55
	s_nop 0
	global_load_lds_dwordx4 v143, s[34:35]
	s_mov_b32 m0, s36
	s_waitcnt vmcnt(8)
	s_waitcnt lgkmcnt(0)
	s_barrier
	s_setprio 1
	s_waitcnt lgkmcnt(7)
	v_mfma_f32_16x16x32_bf16 v[60:63], v[132:135], v[176:179], v[60:63]
	v_mfma_f32_16x16x32_bf16 v[48:51], v[152:155], v[176:179], v[48:51]
	s_waitcnt lgkmcnt(5)
	v_mfma_f32_16x16x32_bf16 v[32:35], v[152:155], v[186:189], v[32:35]
	v_mfma_f32_16x16x32_bf16 v[40:43], v[132:135], v[186:189], v[40:43]
	s_waitcnt lgkmcnt(3)
	v_mfma_f32_16x16x32_bf16 v[24:27], v[132:135], v[194:197], v[24:27]
	v_mfma_f32_16x16x32_bf16 v[16:19], v[152:155], v[194:197], v[16:19]
	s_waitcnt lgkmcnt(1)
	v_mfma_f32_16x16x32_bf16 v[0:3], v[152:155], v[202:205], v[0:3]
	v_mfma_f32_16x16x32_bf16 v[8:11], v[132:135], v[202:205], v[8:11]
	v_mfma_f32_16x16x32_bf16 v[60:63], v[136:139], v[180:183], v[60:63]
	v_mfma_f32_16x16x32_bf16 v[48:51], v[156:159], v[180:183], v[48:51]
	v_mfma_f32_16x16x32_bf16 v[32:35], v[156:159], v[190:193], v[32:35]
	v_mfma_f32_16x16x32_bf16 v[40:43], v[136:139], v[190:193], v[40:43]
	v_mfma_f32_16x16x32_bf16 v[24:27], v[136:139], v[198:201], v[24:27]
	v_mfma_f32_16x16x32_bf16 v[16:19], v[156:159], v[198:201], v[16:19]
	s_waitcnt lgkmcnt(0)
	v_mfma_f32_16x16x32_bf16 v[0:3], v[156:159], v[206:209], v[0:3]
	v_mfma_f32_16x16x32_bf16 v[8:11], v[136:139], v[206:209], v[8:11]
	s_setprio 0
	s_setprio 1
	v_mfma_f32_16x16x32_bf16 v[68:71], v[160:163], v[176:179], v[68:71]
	v_mfma_f32_16x16x32_bf16 v[52:55], v[168:171], v[176:179], v[52:55]
	v_mfma_f32_16x16x32_bf16 v[36:39], v[168:171], v[186:189], v[36:39]
	v_mfma_f32_16x16x32_bf16 v[44:47], v[160:163], v[186:189], v[44:47]
	v_mfma_f32_16x16x32_bf16 v[28:31], v[160:163], v[194:197], v[28:31]
	v_mfma_f32_16x16x32_bf16 v[20:23], v[168:171], v[194:197], v[20:23]
	v_mfma_f32_16x16x32_bf16 v[4:7], v[168:171], v[202:205], v[4:7]
	v_mfma_f32_16x16x32_bf16 v[12:15], v[160:163], v[202:205], v[12:15]
	v_mfma_f32_16x16x32_bf16 v[68:71], v[164:167], v[180:183], v[68:71]
	v_mfma_f32_16x16x32_bf16 v[52:55], v[172:175], v[180:183], v[52:55]
	v_mfma_f32_16x16x32_bf16 v[36:39], v[172:175], v[190:193], v[36:39]
	v_mfma_f32_16x16x32_bf16 v[44:47], v[164:167], v[190:193], v[44:47]
	v_mfma_f32_16x16x32_bf16 v[28:31], v[164:167], v[198:201], v[28:31]
	v_mfma_f32_16x16x32_bf16 v[20:23], v[172:175], v[198:201], v[20:23]
	v_mfma_f32_16x16x32_bf16 v[4:7], v[172:175], v[206:209], v[4:7]
	v_mfma_f32_16x16x32_bf16 v[12:15], v[164:167], v[206:209], v[12:15]
	s_setprio 0
	s_barrier
	s_add_i32 s87, s87, 2
	s_add_u32 s85, s85, 0x100
	s_addc_u32 s86, s86, 0
	s_cmp_gt_u32 s87, 13
	s_mov_b64 s[36:37], s[26:27]
	s_cbranch_scc0 .LBB0_524
	s_and_b64 vcc, exec, s[14:15]
	s_cbranch_vccz .LBB0_527
	s_barrier

.LBB0_659:
	ds_read_b128 v[80:83], v198
	ds_read_b128 v[84:87], v198 offset:1024
	ds_read_b128 v[104:107], v198 offset:2048
	ds_read_b128 v[108:111], v198 offset:3072
	ds_read_b128 v[128:131], v199
	ds_read_b128 v[132:135], v199 offset:1024
	ds_read_b128 v[152:155], v199 offset:2048
	ds_read_b128 v[156:159], v199 offset:3072
	s_add_u32 s10, s42, 0x100
	s_addc_u32 s11, s43, 0
	s_cmp_eq_u32 s86, 40
	s_cselect_b32 s50, s36, s10
	s_cselect_b32 s51, s37, s11
	s_cselect_b32 s48, s38, s84
	s_cselect_b32 s49, s39, s85
	s_add_u32 s40, s50, 0x80
	s_addc_u32 s41, s51, 0
	ds_read_b128 v[160:163], v200
	ds_read_b128 v[164:167], v200 offset:1024
	ds_read_b128 v[168:171], v200 offset:2048
	ds_read_b128 v[172:175], v200 offset:3072
	ds_read_b128 v[176:179], v200 offset:4096
	ds_read_b128 v[180:183], v200 offset:5120
	ds_read_b128 v[188:191], v200 offset:6144
	ds_read_b128 v[204:207], v200 offset:7168
	s_add_u32 s42, s42, 0xb0080
	s_addc_u32 s43, s43, 0
	s_mov_b32 s58, m0
	s_mov_b32 m0, s70
	s_nop 0
	global_load_lds_dwordx4 v194, s[42:43]
	s_mov_b32 m0, s58
	s_nop 0
	s_mov_b32 s58, m0
	s_mov_b32 m0, s73
	s_nop 0
	global_load_lds_dwordx4 v195, s[42:43]
	s_mov_b32 m0, s58
	s_waitcnt vmcnt(8)
	s_waitcnt lgkmcnt(0)
	s_barrier
	s_setprio 1
	s_waitcnt lgkmcnt(7)
	v_mfma_f32_16x16x32_bf16 v[136:139], v[80:83], v[160:163], v[136:139]
	v_mfma_f32_16x16x32_bf16 v[140:143], v[104:107], v[160:163], v[140:143]
	s_waitcnt lgkmcnt(5)
	v_mfma_f32_16x16x32_bf16 v[120:123], v[104:107], v[168:171], v[120:123]
	v_mfma_f32_16x16x32_bf16 v[124:127], v[80:83], v[168:171], v[124:127]
	s_waitcnt lgkmcnt(3)
	v_mfma_f32_16x16x32_bf16 v[100:103], v[80:83], v[176:179], v[100:103]
	v_mfma_f32_16x16x32_bf16 v[96:99], v[104:107], v[176:179], v[96:99]
	s_waitcnt lgkmcnt(1)
	v_mfma_f32_16x16x32_bf16 v[72:75], v[104:107], v[188:191], v[72:75]
	v_mfma_f32_16x16x32_bf16 v[76:79], v[80:83], v[188:191], v[76:79]
	v_mfma_f32_16x16x32_bf16 v[136:139], v[84:87], v[164:167], v[136:139]
	v_mfma_f32_16x16x32_bf16 v[140:143], v[108:111], v[164:167], v[140:143]
	v_mfma_f32_16x16x32_bf16 v[120:123], v[108:111], v[172:175], v[120:123]
	v_mfma_f32_16x16x32_bf16 v[124:127], v[84:87], v[172:175], v[124:127]
	v_mfma_f32_16x16x32_bf16 v[100:103], v[84:87], v[180:183], v[100:103]
	v_mfma_f32_16x16x32_bf16 v[96:99], v[108:111], v[180:183], v[96:99]
	s_waitcnt lgkmcnt(0)
	v_mfma_f32_16x16x32_bf16 v[72:75], v[108:111], v[204:207], v[72:75]
	v_mfma_f32_16x16x32_bf16 v[76:79], v[84:87], v[204:207], v[76:79]
	s_setprio 0
	s_setprio 1
	v_mfma_f32_16x16x32_bf16 v[148:151], v[128:131], v[160:163], v[148:151]
	v_mfma_f32_16x16x32_bf16 v[144:147], v[152:155], v[160:163], v[144:147]
	v_mfma_f32_16x16x32_bf16 v[112:115], v[152:155], v[168:171], v[112:115]
	v_mfma_f32_16x16x32_bf16 v[116:119], v[128:131], v[168:171], v[116:119]
	v_mfma_f32_16x16x32_bf16 v[92:95], v[128:131], v[176:179], v[92:95]
	v_mfma_f32_16x16x32_bf16 v[88:91], v[152:155], v[176:179], v[88:91]
	v_mfma_f32_16x16x32_bf16 v[64:67], v[152:155], v[188:191], v[64:67]
	v_mfma_f32_16x16x32_bf16 v[68:71], v[128:131], v[188:191], v[68:71]
	v_mfma_f32_16x16x32_bf16 v[148:151], v[132:135], v[164:167], v[148:151]
	v_mfma_f32_16x16x32_bf16 v[144:147], v[156:159], v[164:167], v[144:147]
	v_mfma_f32_16x16x32_bf16 v[112:115], v[156:159], v[172:175], v[112:115]
	v_mfma_f32_16x16x32_bf16 v[116:119], v[132:135], v[172:175], v[116:119]
	v_mfma_f32_16x16x32_bf16 v[92:95], v[132:135], v[180:183], v[92:95]
	v_mfma_f32_16x16x32_bf16 v[88:91], v[156:159], v[180:183], v[88:91]
	v_mfma_f32_16x16x32_bf16 v[64:67], v[156:159], v[204:207], v[64:67]
	v_mfma_f32_16x16x32_bf16 v[68:71], v[132:135], v[204:207], v[68:71]
	s_setprio 0
	s_barrier
	ds_read_b128 v[160:163], v200 offset:16384
	ds_read_b128 v[164:167], v200 offset:17408
	ds_read_b128 v[168:171], v200 offset:18432
	ds_read_b128 v[172:175], v200 offset:19456
	ds_read_b128 v[176:179], v200 offset:20480
	ds_read_b128 v[180:183], v200 offset:21504
	ds_read_b128 v[188:191], v200 offset:22528
	ds_read_b128 v[204:207], v200 offset:23552
	s_mov_b32 s42, m0
	s_mov_b32 m0, s71
	s_nop 0
	global_load_lds_dwordx4 v192, s[48:49]
	s_mov_b32 m0, s42
	s_nop 0
	s_mov_b32 s42, m0
	s_mov_b32 m0, s74
	s_nop 0
	global_load_lds_dwordx4 v193, s[48:49]
	s_mov_b32 m0, s42
	s_add_u32 s42, s48, 0xb0000
	s_addc_u32 s43, s49, 0
	s_mov_b32 s58, m0
	s_mov_b32 m0, s72
	s_nop 0
	global_load_lds_dwordx4 v192, s[42:43]
	s_mov_b32 m0, s58
	s_nop 0
	s_mov_b32 s58, m0
	s_mov_b32 m0, s75
	s_nop 0
	global_load_lds_dwordx4 v193, s[42:43]
	s_mov_b32 m0, s58
	s_mov_b32 s42, m0
	s_mov_b32 m0, s4
	s_nop 0
	global_load_lds_dwordx4 v194, s[50:51]
	s_mov_b32 m0, s42
	s_nop 0
	s_mov_b32 s42, m0
	s_mov_b32 m0, s5
	s_nop 0
	global_load_lds_dwordx4 v195, s[50:51]
	s_mov_b32 m0, s42
	s_waitcnt vmcnt(8)
	s_waitcnt lgkmcnt(0)
	s_barrier
	s_setprio 1
	s_waitcnt lgkmcnt(7)
	v_mfma_f32_16x16x32_bf16 v[60:63], v[80:83], v[160:163], v[60:63]
	v_mfma_f32_16x16x32_bf16 v[56:59], v[104:107], v[160:163], v[56:59]
	s_waitcnt lgkmcnt(5)
	v_mfma_f32_16x16x32_bf16 v[40:43], v[104:107], v[168:171], v[40:43]
	v_mfma_f32_16x16x32_bf16 v[44:47], v[80:83], v[168:171], v[44:47]
	s_waitcnt lgkmcnt(3)
	v_mfma_f32_16x16x32_bf16 v[28:31], v[80:83], v[176:179], v[28:31]
	v_mfma_f32_16x16x32_bf16 v[24:27], v[104:107], v[176:179], v[24:27]
	s_waitcnt lgkmcnt(1)
	v_mfma_f32_16x16x32_bf16 v[8:11], v[104:107], v[188:191], v[8:11]
	v_mfma_f32_16x16x32_bf16 v[12:15], v[80:83], v[188:191], v[12:15]
	v_mfma_f32_16x16x32_bf16 v[60:63], v[84:87], v[164:167], v[60:63]
	v_mfma_f32_16x16x32_bf16 v[56:59], v[108:111], v[164:167], v[56:59]
	v_mfma_f32_16x16x32_bf16 v[40:43], v[108:111], v[172:175], v[40:43]
	v_mfma_f32_16x16x32_bf16 v[44:47], v[84:87], v[172:175], v[44:47]
	v_mfma_f32_16x16x32_bf16 v[28:31], v[84:87], v[180:183], v[28:31]
	v_mfma_f32_16x16x32_bf16 v[24:27], v[108:111], v[180:183], v[24:27]
	s_waitcnt lgkmcnt(0)
	v_mfma_f32_16x16x32_bf16 v[8:11], v[108:111], v[204:207], v[8:11]
	v_mfma_f32_16x16x32_bf16 v[12:15], v[84:87], v[204:207], v[12:15]
	s_setprio 0
	s_setprio 1
	v_mfma_f32_16x16x32_bf16 v[52:55], v[128:131], v[160:163], v[52:55]
	v_mfma_f32_16x16x32_bf16 v[48:51], v[152:155], v[160:163], v[48:51]
	v_mfma_f32_16x16x32_bf16 v[32:35], v[152:155], v[168:171], v[32:35]
	v_mfma_f32_16x16x32_bf16 v[36:39], v[128:131], v[168:171], v[36:39]
	v_mfma_f32_16x16x32_bf16 v[20:23], v[128:131], v[176:179], v[20:23]
	v_mfma_f32_16x16x32_bf16 v[16:19], v[152:155], v[176:179], v[16:19]
	v_mfma_f32_16x16x32_bf16 v[0:3], v[152:155], v[188:191], v[0:3]
	v_mfma_f32_16x16x32_bf16 v[4:7], v[128:131], v[188:191], v[4:7]
	v_mfma_f32_16x16x32_bf16 v[52:55], v[132:135], v[164:167], v[52:55]
	v_mfma_f32_16x16x32_bf16 v[48:51], v[156:159], v[164:167], v[48:51]
	v_mfma_f32_16x16x32_bf16 v[32:35], v[156:159], v[172:175], v[32:35]
	v_mfma_f32_16x16x32_bf16 v[36:39], v[132:135], v[172:175], v[36:39]
	v_mfma_f32_16x16x32_bf16 v[20:23], v[132:135], v[180:183], v[20:23]
	v_mfma_f32_16x16x32_bf16 v[16:19], v[156:159], v[180:183], v[16:19]
	v_mfma_f32_16x16x32_bf16 v[0:3], v[156:159], v[204:207], v[0:3]
	v_mfma_f32_16x16x32_bf16 v[4:7], v[132:135], v[204:207], v[4:7]
	s_setprio 0
	s_barrier
	ds_read_b128 v[80:83], v201
	ds_read_b128 v[84:87], v201 offset:1024
	ds_read_b128 v[104:107], v201 offset:2048
	ds_read_b128 v[108:111], v201 offset:3072
	ds_read_b128 v[128:131], v202
	ds_read_b128 v[132:135], v202 offset:1024
	ds_read_b128 v[152:155], v202 offset:2048
	ds_read_b128 v[156:159], v202 offset:3072
	ds_read_b128 v[160:163], v200 offset:32768
	ds_read_b128 v[164:167], v200 offset:33792
	ds_read_b128 v[168:171], v200 offset:34816
	ds_read_b128 v[172:175], v200 offset:35840
	ds_read_b128 v[176:179], v200 offset:36864
	ds_read_b128 v[180:183], v200 offset:37888
	ds_read_b128 v[188:191], v200 offset:38912
	ds_read_b128 v[204:207], v200 offset:39936
	s_add_u32 s42, s50, 0xb0000
	s_addc_u32 s43, s51, 0
	s_mov_b32 s50, m0
	s_mov_b32 m0, s33
	s_nop 0
	global_load_lds_dwordx4 v194, s[42:43]
	s_mov_b32 m0, s50
	s_nop 0
	s_mov_b32 s50, m0
	s_mov_b32 m0, s52
	s_nop 0
	global_load_lds_dwordx4 v195, s[42:43]
	s_mov_b32 m0, s50
	s_waitcnt vmcnt(8)
	s_waitcnt lgkmcnt(0)
	s_barrier
	s_setprio 1
	s_waitcnt lgkmcnt(7)
	v_mfma_f32_16x16x32_bf16 v[136:139], v[80:83], v[160:163], v[136:139]
	v_mfma_f32_16x16x32_bf16 v[140:143], v[104:107], v[160:163], v[140:143]
	s_waitcnt lgkmcnt(5)
	v_mfma_f32_16x16x32_bf16 v[120:123], v[104:107], v[168:171], v[120:123]
	v_mfma_f32_16x16x32_bf16 v[124:127], v[80:83], v[168:171], v[124:127]
	s_waitcnt lgkmcnt(3)
	v_mfma_f32_16x16x32_bf16 v[100:103], v[80:83], v[176:179], v[100:103]
	v_mfma_f32_16x16x32_bf16 v[96:99], v[104:107], v[176:179], v[96:99]
	s_waitcnt lgkmcnt(1)
	v_mfma_f32_16x16x32_bf16 v[72:75], v[104:107], v[188:191], v[72:75]
	v_mfma_f32_16x16x32_bf16 v[76:79], v[80:83], v[188:191], v[76:79]
	v_mfma_f32_16x16x32_bf16 v[136:139], v[84:87], v[164:167], v[136:139]
	v_mfma_f32_16x16x32_bf16 v[140:143], v[108:111], v[164:167], v[140:143]
	v_mfma_f32_16x16x32_bf16 v[120:123], v[108:111], v[172:175], v[120:123]
	v_mfma_f32_16x16x32_bf16 v[124:127], v[84:87], v[172:175], v[124:127]
	v_mfma_f32_16x16x32_bf16 v[100:103], v[84:87], v[180:183], v[100:103]
	v_mfma_f32_16x16x32_bf16 v[96:99], v[108:111], v[180:183], v[96:99]
	s_waitcnt lgkmcnt(0)
	v_mfma_f32_16x16x32_bf16 v[72:75], v[108:111], v[204:207], v[72:75]
	v_mfma_f32_16x16x32_bf16 v[76:79], v[84:87], v[204:207], v[76:79]
	s_setprio 0
	s_setprio 1
	v_mfma_f32_16x16x32_bf16 v[148:151], v[128:131], v[160:163], v[148:151]
	v_mfma_f32_16x16x32_bf16 v[144:147], v[152:155], v[160:163], v[144:147]
	v_mfma_f32_16x16x32_bf16 v[112:115], v[152:155], v[168:171], v[112:115]
	v_mfma_f32_16x16x32_bf16 v[116:119], v[128:131], v[168:171], v[116:119]
	v_mfma_f32_16x16x32_bf16 v[92:95], v[128:131], v[176:179], v[92:95]
	v_mfma_f32_16x16x32_bf16 v[88:91], v[152:155], v[176:179], v[88:91]
	v_mfma_f32_16x16x32_bf16 v[64:67], v[152:155], v[188:191], v[64:67]
	v_mfma_f32_16x16x32_bf16 v[68:71], v[128:131], v[188:191], v[68:71]
	v_mfma_f32_16x16x32_bf16 v[148:151], v[132:135], v[164:167], v[148:151]
	v_mfma_f32_16x16x32_bf16 v[144:147], v[156:159], v[164:167], v[144:147]
	v_mfma_f32_16x16x32_bf16 v[112:115], v[156:159], v[172:175], v[112:115]
	v_mfma_f32_16x16x32_bf16 v[116:119], v[132:135], v[172:175], v[116:119]
	v_mfma_f32_16x16x32_bf16 v[92:95], v[132:135], v[180:183], v[92:95]
	v_mfma_f32_16x16x32_bf16 v[88:91], v[156:159], v[180:183], v[88:91]
	v_mfma_f32_16x16x32_bf16 v[64:67], v[156:159], v[204:207], v[64:67]
	v_mfma_f32_16x16x32_bf16 v[68:71], v[132:135], v[204:207], v[68:71]
	s_setprio 0
	s_barrier
	ds_read_b128 v[160:163], v200 offset:49152
	ds_read_b128 v[164:167], v200 offset:50176
	ds_read_b128 v[168:171], v200 offset:51200
	ds_read_b128 v[172:175], v200 offset:52224
	ds_read_b128 v[176:179], v200 offset:53248
	ds_read_b128 v[180:183], v200 offset:54272
	ds_read_b128 v[188:191], v200 offset:55296
	ds_read_b128 v[204:207], v200 offset:56320
	s_add_u32 s42, s48, 0x80
	s_addc_u32 s43, s49, 0
	s_mov_b32 s50, m0
	s_mov_b32 m0, s54
	s_nop 0
	global_load_lds_dwordx4 v192, s[42:43]
	s_mov_b32 m0, s50
	s_nop 0
	s_mov_b32 s50, m0
	s_mov_b32 m0, s55
	s_nop 0
	global_load_lds_dwordx4 v193, s[42:43]
	s_mov_b32 m0, s50
	s_add_u32 s42, s48, 0xb0080
	s_addc_u32 s43, s49, 0
	s_mov_b32 s48, m0
	s_mov_b32 m0, s68
	s_nop 0
	global_load_lds_dwordx4 v192, s[42:43]
	s_mov_b32 m0, s48
	s_nop 0
	s_mov_b32 s48, m0
	s_mov_b32 m0, s69
	s_nop 0
	global_load_lds_dwordx4 v193, s[42:43]
	s_mov_b32 m0, s48
	s_mov_b32 s42, m0
	s_mov_b32 m0, s62
	s_nop 0
	global_load_lds_dwordx4 v194, s[40:41]
	s_mov_b32 m0, s42
	s_nop 0
	s_mov_b32 s42, m0
	s_mov_b32 m0, s63
	s_nop 0
	global_load_lds_dwordx4 v195, s[40:41]
	s_mov_b32 m0, s42
	s_waitcnt vmcnt(8)
	s_waitcnt lgkmcnt(0)
	s_barrier
	s_setprio 1
	s_waitcnt lgkmcnt(7)
	v_mfma_f32_16x16x32_bf16 v[60:63], v[80:83], v[160:163], v[60:63]
	v_mfma_f32_16x16x32_bf16 v[56:59], v[104:107], v[160:163], v[56:59]
	s_waitcnt lgkmcnt(5)
	v_mfma_f32_16x16x32_bf16 v[40:43], v[104:107], v[168:171], v[40:43]
	v_mfma_f32_16x16x32_bf16 v[44:47], v[80:83], v[168:171], v[44:47]
	s_waitcnt lgkmcnt(3)
	v_mfma_f32_16x16x32_bf16 v[28:31], v[80:83], v[176:179], v[28:31]
	v_mfma_f32_16x16x32_bf16 v[24:27], v[104:107], v[176:179], v[24:27]
	s_waitcnt lgkmcnt(1)
	v_mfma_f32_16x16x32_bf16 v[8:11], v[104:107], v[188:191], v[8:11]
	v_mfma_f32_16x16x32_bf16 v[12:15], v[80:83], v[188:191], v[12:15]
	v_mfma_f32_16x16x32_bf16 v[60:63], v[84:87], v[164:167], v[60:63]
	v_mfma_f32_16x16x32_bf16 v[56:59], v[108:111], v[164:167], v[56:59]
	v_mfma_f32_16x16x32_bf16 v[40:43], v[108:111], v[172:175], v[40:43]
	v_mfma_f32_16x16x32_bf16 v[44:47], v[84:87], v[172:175], v[44:47]
	v_mfma_f32_16x16x32_bf16 v[28:31], v[84:87], v[180:183], v[28:31]
	v_mfma_f32_16x16x32_bf16 v[24:27], v[108:111], v[180:183], v[24:27]
	s_waitcnt lgkmcnt(0)
	v_mfma_f32_16x16x32_bf16 v[8:11], v[108:111], v[204:207], v[8:11]
	v_mfma_f32_16x16x32_bf16 v[12:15], v[84:87], v[204:207], v[12:15]
	s_setprio 0
	s_setprio 1
	v_mfma_f32_16x16x32_bf16 v[52:55], v[128:131], v[160:163], v[52:55]
	v_mfma_f32_16x16x32_bf16 v[48:51], v[152:155], v[160:163], v[48:51]
	v_mfma_f32_16x16x32_bf16 v[32:35], v[152:155], v[168:171], v[32:35]
	v_mfma_f32_16x16x32_bf16 v[36:39], v[128:131], v[168:171], v[36:39]
	v_mfma_f32_16x16x32_bf16 v[20:23], v[128:131], v[176:179], v[20:23]
	v_mfma_f32_16x16x32_bf16 v[16:19], v[152:155], v[176:179], v[16:19]
	v_mfma_f32_16x16x32_bf16 v[0:3], v[152:155], v[188:191], v[0:3]
	v_mfma_f32_16x16x32_bf16 v[4:7], v[128:131], v[188:191], v[4:7]
	v_mfma_f32_16x16x32_bf16 v[52:55], v[132:135], v[164:167], v[52:55]
	v_mfma_f32_16x16x32_bf16 v[48:51], v[156:159], v[164:167], v[48:51]
	v_mfma_f32_16x16x32_bf16 v[32:35], v[156:159], v[172:175], v[32:35]
	v_mfma_f32_16x16x32_bf16 v[36:39], v[132:135], v[172:175], v[36:39]
	v_mfma_f32_16x16x32_bf16 v[20:23], v[132:135], v[180:183], v[20:23]
	v_mfma_f32_16x16x32_bf16 v[16:19], v[156:159], v[180:183], v[16:19]
	v_mfma_f32_16x16x32_bf16 v[0:3], v[156:159], v[204:207], v[0:3]
	v_mfma_f32_16x16x32_bf16 v[4:7], v[132:135], v[204:207], v[4:7]
	s_setprio 0
	s_barrier
	s_add_i32 s86, s86, 2
	s_add_u32 s84, s84, 0x100
	s_addc_u32 s85, s85, 0
	s_cmp_gt_u32 s86, 41
	s_mov_b64 s[42:43], s[10:11]
	s_cbranch_scc0 .LBB0_659
	s_and_b64 vcc, exec, s[22:23]
	s_cbranch_vccz .LBB0_662
	s_barrier

.LBB0_784:
	ds_read_b128 v[128:131], v178
	ds_read_b128 v[132:135], v178 offset:1024
	ds_read_b128 v[136:139], v178 offset:2048
	ds_read_b128 v[140:143], v178 offset:3072
	ds_read_b128 v[152:155], v179
	ds_read_b128 v[158:161], v179 offset:1024
	ds_read_b128 v[162:165], v179 offset:2048
	ds_read_b128 v[166:169], v179 offset:3072
	s_add_u32 s36, s40, 0x100
	s_addc_u32 s37, s41, 0
	s_cmp_eq_u32 s90, 12
	s_cselect_b32 s48, s27, s36
	s_cselect_b32 s49, s25, s37
	s_cselect_b32 s42, s86, s87
	s_cselect_b32 s43, s35, s89
	s_add_u32 s38, s48, 0x80
	s_addc_u32 s39, s49, 0
	ds_read_b128 v[170:173], v180
	ds_read_b128 v[188:191], v180 offset:1024
	ds_read_b128 v[192:195], v180 offset:2048
	ds_read_b128 v[196:199], v180 offset:3072
	ds_read_b128 v[200:203], v180 offset:4096
	ds_read_b128 v[204:207], v180 offset:5120
	ds_read_b128 v[208:211], v180 offset:6144
	ds_read_b128 v[212:215], v180 offset:7168
	s_add_u32 s40, s40, 0x40080
	s_addc_u32 s41, s41, 0
	s_mov_b32 s58, m0
	s_mov_b32 m0, s72
	s_nop 0
	global_load_lds_dwordx4 v151, s[40:41]
	s_mov_b32 m0, s58
	s_nop 0
	s_mov_b32 s58, m0
	s_mov_b32 m0, s75
	s_nop 0
	global_load_lds_dwordx4 v174, s[40:41]
	s_mov_b32 m0, s58
	s_waitcnt vmcnt(8)
	s_waitcnt lgkmcnt(0)
	s_barrier
	s_setprio 1
	s_waitcnt lgkmcnt(7)
	v_mfma_f32_16x16x32_bf16 v[120:123], v[128:131], v[170:173], v[120:123]
	v_mfma_f32_16x16x32_bf16 v[112:115], v[136:139], v[170:173], v[112:115]
	s_waitcnt lgkmcnt(5)
	v_mfma_f32_16x16x32_bf16 v[104:107], v[136:139], v[192:195], v[104:107]
	v_mfma_f32_16x16x32_bf16 v[108:111], v[128:131], v[192:195], v[108:111]
	s_waitcnt lgkmcnt(3)
	v_mfma_f32_16x16x32_bf16 v[92:95], v[128:131], v[200:203], v[92:95]
	v_mfma_f32_16x16x32_bf16 v[88:91], v[136:139], v[200:203], v[88:91]
	s_waitcnt lgkmcnt(1)
	v_mfma_f32_16x16x32_bf16 v[56:59], v[136:139], v[208:211], v[56:59]
	v_mfma_f32_16x16x32_bf16 v[60:63], v[128:131], v[208:211], v[60:63]
	v_mfma_f32_16x16x32_bf16 v[120:123], v[132:135], v[188:191], v[120:123]
	v_mfma_f32_16x16x32_bf16 v[112:115], v[140:143], v[188:191], v[112:115]
	v_mfma_f32_16x16x32_bf16 v[104:107], v[140:143], v[196:199], v[104:107]
	v_mfma_f32_16x16x32_bf16 v[108:111], v[132:135], v[196:199], v[108:111]
	v_mfma_f32_16x16x32_bf16 v[92:95], v[132:135], v[204:207], v[92:95]
	v_mfma_f32_16x16x32_bf16 v[88:91], v[140:143], v[204:207], v[88:91]
	s_waitcnt lgkmcnt(0)
	v_mfma_f32_16x16x32_bf16 v[56:59], v[140:143], v[212:215], v[56:59]
	v_mfma_f32_16x16x32_bf16 v[60:63], v[132:135], v[212:215], v[60:63]
	s_setprio 0
	s_setprio 1
	v_mfma_f32_16x16x32_bf16 v[124:127], v[152:155], v[170:173], v[124:127]
	v_mfma_f32_16x16x32_bf16 v[116:119], v[162:165], v[170:173], v[116:119]
	v_mfma_f32_16x16x32_bf16 v[96:99], v[162:165], v[192:195], v[96:99]
	v_mfma_f32_16x16x32_bf16 v[100:103], v[152:155], v[192:195], v[100:103]
	v_mfma_f32_16x16x32_bf16 v[84:87], v[152:155], v[200:203], v[84:87]
	v_mfma_f32_16x16x32_bf16 v[80:83], v[162:165], v[200:203], v[80:83]
	v_mfma_f32_16x16x32_bf16 v[48:51], v[162:165], v[208:211], v[48:51]
	v_mfma_f32_16x16x32_bf16 v[52:55], v[152:155], v[208:211], v[52:55]
	v_mfma_f32_16x16x32_bf16 v[124:127], v[158:161], v[188:191], v[124:127]
	v_mfma_f32_16x16x32_bf16 v[116:119], v[166:169], v[188:191], v[116:119]
	v_mfma_f32_16x16x32_bf16 v[96:99], v[166:169], v[196:199], v[96:99]
	v_mfma_f32_16x16x32_bf16 v[100:103], v[158:161], v[196:199], v[100:103]
	v_mfma_f32_16x16x32_bf16 v[84:87], v[158:161], v[204:207], v[84:87]
	v_mfma_f32_16x16x32_bf16 v[80:83], v[166:169], v[204:207], v[80:83]
	v_mfma_f32_16x16x32_bf16 v[48:51], v[166:169], v[212:215], v[48:51]
	v_mfma_f32_16x16x32_bf16 v[52:55], v[158:161], v[212:215], v[52:55]
	s_setprio 0
	s_barrier
	ds_read_b128 v[170:173], v180 offset:16384
	ds_read_b128 v[188:191], v180 offset:17408
	ds_read_b128 v[192:195], v180 offset:18432
	ds_read_b128 v[196:199], v180 offset:19456
	ds_read_b128 v[200:203], v180 offset:20480
	ds_read_b128 v[204:207], v180 offset:21504
	ds_read_b128 v[208:211], v180 offset:22528
	ds_read_b128 v[212:215], v180 offset:23552
	s_mov_b32 s40, m0
	s_mov_b32 m0, s73
	s_nop 0
	global_load_lds_dwordx4 v147, s[42:43]
	s_mov_b32 m0, s40
	s_nop 0
	s_mov_b32 s40, m0
	s_mov_b32 m0, s76
	s_nop 0
	global_load_lds_dwordx4 v149, s[42:43]
	s_mov_b32 m0, s40
	s_add_u32 s40, s42, 0x40000
	s_addc_u32 s41, s43, 0
	s_mov_b32 s58, m0
	s_mov_b32 m0, s74
	s_nop 0
	global_load_lds_dwordx4 v147, s[40:41]
	s_mov_b32 m0, s58
	s_nop 0
	s_mov_b32 s58, m0
	s_mov_b32 m0, s78
	s_nop 0
	global_load_lds_dwordx4 v149, s[40:41]
	s_mov_b32 m0, s58
	s_mov_b32 s40, m0
	s_mov_b32 m0, s53
	s_nop 0
	global_load_lds_dwordx4 v151, s[48:49]
	s_mov_b32 m0, s40
	s_nop 0
	s_mov_b32 s40, m0
	s_mov_b32 m0, s54
	s_nop 0
	global_load_lds_dwordx4 v174, s[48:49]
	s_mov_b32 m0, s40
	s_waitcnt vmcnt(8)
	s_waitcnt lgkmcnt(0)
	s_barrier
	s_setprio 1
	s_waitcnt lgkmcnt(7)
	v_mfma_f32_16x16x32_bf16 v[76:79], v[128:131], v[170:173], v[76:79]
	v_mfma_f32_16x16x32_bf16 v[72:75], v[136:139], v[170:173], v[72:75]
	s_waitcnt lgkmcnt(5)
	v_mfma_f32_16x16x32_bf16 v[40:43], v[136:139], v[192:195], v[40:43]
	v_mfma_f32_16x16x32_bf16 v[44:47], v[128:131], v[192:195], v[44:47]
	s_waitcnt lgkmcnt(3)
	v_mfma_f32_16x16x32_bf16 v[28:31], v[128:131], v[200:203], v[28:31]
	v_mfma_f32_16x16x32_bf16 v[24:27], v[136:139], v[200:203], v[24:27]
	s_waitcnt lgkmcnt(1)
	v_mfma_f32_16x16x32_bf16 v[8:11], v[136:139], v[208:211], v[8:11]
	v_mfma_f32_16x16x32_bf16 v[12:15], v[128:131], v[208:211], v[12:15]
	v_mfma_f32_16x16x32_bf16 v[76:79], v[132:135], v[188:191], v[76:79]
	v_mfma_f32_16x16x32_bf16 v[72:75], v[140:143], v[188:191], v[72:75]
	v_mfma_f32_16x16x32_bf16 v[40:43], v[140:143], v[196:199], v[40:43]
	v_mfma_f32_16x16x32_bf16 v[44:47], v[132:135], v[196:199], v[44:47]
	v_mfma_f32_16x16x32_bf16 v[28:31], v[132:135], v[204:207], v[28:31]
	v_mfma_f32_16x16x32_bf16 v[24:27], v[140:143], v[204:207], v[24:27]
	s_waitcnt lgkmcnt(0)
	v_mfma_f32_16x16x32_bf16 v[8:11], v[140:143], v[212:215], v[8:11]
	v_mfma_f32_16x16x32_bf16 v[12:15], v[132:135], v[212:215], v[12:15]
	s_setprio 0
	s_setprio 1
	v_mfma_f32_16x16x32_bf16 v[68:71], v[152:155], v[170:173], v[68:71]
	v_mfma_f32_16x16x32_bf16 v[64:67], v[162:165], v[170:173], v[64:67]
	v_mfma_f32_16x16x32_bf16 v[32:35], v[162:165], v[192:195], v[32:35]
	v_mfma_f32_16x16x32_bf16 v[36:39], v[152:155], v[192:195], v[36:39]
	v_mfma_f32_16x16x32_bf16 v[20:23], v[152:155], v[200:203], v[20:23]
	v_mfma_f32_16x16x32_bf16 v[16:19], v[162:165], v[200:203], v[16:19]
	v_mfma_f32_16x16x32_bf16 v[0:3], v[162:165], v[208:211], v[0:3]
	v_mfma_f32_16x16x32_bf16 v[4:7], v[152:155], v[208:211], v[4:7]
	v_mfma_f32_16x16x32_bf16 v[68:71], v[158:161], v[188:191], v[68:71]
	v_mfma_f32_16x16x32_bf16 v[64:67], v[166:169], v[188:191], v[64:67]
	v_mfma_f32_16x16x32_bf16 v[32:35], v[166:169], v[196:199], v[32:35]
	v_mfma_f32_16x16x32_bf16 v[36:39], v[158:161], v[196:199], v[36:39]
	v_mfma_f32_16x16x32_bf16 v[20:23], v[158:161], v[204:207], v[20:23]
	v_mfma_f32_16x16x32_bf16 v[16:19], v[166:169], v[204:207], v[16:19]
	v_mfma_f32_16x16x32_bf16 v[0:3], v[166:169], v[212:215], v[0:3]
	v_mfma_f32_16x16x32_bf16 v[4:7], v[158:161], v[212:215], v[4:7]
	s_setprio 0
	s_barrier
	ds_read_b128 v[128:131], v181
	ds_read_b128 v[132:135], v181 offset:1024
	ds_read_b128 v[136:139], v181 offset:2048
	ds_read_b128 v[140:143], v181 offset:3072
	ds_read_b128 v[152:155], v182
	ds_read_b128 v[158:161], v182 offset:1024
	ds_read_b128 v[162:165], v182 offset:2048
	ds_read_b128 v[166:169], v182 offset:3072
	ds_read_b128 v[170:173], v180 offset:32768
	ds_read_b128 v[188:191], v180 offset:33792
	ds_read_b128 v[192:195], v180 offset:34816
	ds_read_b128 v[196:199], v180 offset:35840
	ds_read_b128 v[200:203], v180 offset:36864
	ds_read_b128 v[204:207], v180 offset:37888
	ds_read_b128 v[208:211], v180 offset:38912
	ds_read_b128 v[212:215], v180 offset:39936
	s_add_u32 s40, s48, 0x40000
	s_addc_u32 s41, s49, 0
	s_mov_b32 s48, m0
	s_mov_b32 m0, s55
	s_nop 0
	global_load_lds_dwordx4 v151, s[40:41]
	s_mov_b32 m0, s48
	s_nop 0
	s_mov_b32 s48, m0
	s_mov_b32 m0, s62
	s_nop 0
	global_load_lds_dwordx4 v174, s[40:41]
	s_mov_b32 m0, s48
	s_waitcnt vmcnt(8)
	s_waitcnt lgkmcnt(0)
	s_barrier
	s_setprio 1
	s_waitcnt lgkmcnt(7)
	v_mfma_f32_16x16x32_bf16 v[120:123], v[128:131], v[170:173], v[120:123]
	v_mfma_f32_16x16x32_bf16 v[112:115], v[136:139], v[170:173], v[112:115]
	s_waitcnt lgkmcnt(5)
	v_mfma_f32_16x16x32_bf16 v[104:107], v[136:139], v[192:195], v[104:107]
	v_mfma_f32_16x16x32_bf16 v[108:111], v[128:131], v[192:195], v[108:111]
	s_waitcnt lgkmcnt(3)
	v_mfma_f32_16x16x32_bf16 v[92:95], v[128:131], v[200:203], v[92:95]
	v_mfma_f32_16x16x32_bf16 v[88:91], v[136:139], v[200:203], v[88:91]
	s_waitcnt lgkmcnt(1)
	v_mfma_f32_16x16x32_bf16 v[56:59], v[136:139], v[208:211], v[56:59]
	v_mfma_f32_16x16x32_bf16 v[60:63], v[128:131], v[208:211], v[60:63]
	v_mfma_f32_16x16x32_bf16 v[120:123], v[132:135], v[188:191], v[120:123]
	v_mfma_f32_16x16x32_bf16 v[112:115], v[140:143], v[188:191], v[112:115]
	v_mfma_f32_16x16x32_bf16 v[104:107], v[140:143], v[196:199], v[104:107]
	v_mfma_f32_16x16x32_bf16 v[108:111], v[132:135], v[196:199], v[108:111]
	v_mfma_f32_16x16x32_bf16 v[92:95], v[132:135], v[204:207], v[92:95]
	v_mfma_f32_16x16x32_bf16 v[88:91], v[140:143], v[204:207], v[88:91]
	s_waitcnt lgkmcnt(0)
	v_mfma_f32_16x16x32_bf16 v[56:59], v[140:143], v[212:215], v[56:59]
	v_mfma_f32_16x16x32_bf16 v[60:63], v[132:135], v[212:215], v[60:63]
	s_setprio 0
	s_setprio 1
	v_mfma_f32_16x16x32_bf16 v[124:127], v[152:155], v[170:173], v[124:127]
	v_mfma_f32_16x16x32_bf16 v[116:119], v[162:165], v[170:173], v[116:119]
	v_mfma_f32_16x16x32_bf16 v[96:99], v[162:165], v[192:195], v[96:99]
	v_mfma_f32_16x16x32_bf16 v[100:103], v[152:155], v[192:195], v[100:103]
	v_mfma_f32_16x16x32_bf16 v[84:87], v[152:155], v[200:203], v[84:87]
	v_mfma_f32_16x16x32_bf16 v[80:83], v[162:165], v[200:203], v[80:83]
	v_mfma_f32_16x16x32_bf16 v[48:51], v[162:165], v[208:211], v[48:51]
	v_mfma_f32_16x16x32_bf16 v[52:55], v[152:155], v[208:211], v[52:55]
	v_mfma_f32_16x16x32_bf16 v[124:127], v[158:161], v[188:191], v[124:127]
	v_mfma_f32_16x16x32_bf16 v[116:119], v[166:169], v[188:191], v[116:119]
	v_mfma_f32_16x16x32_bf16 v[96:99], v[166:169], v[196:199], v[96:99]
	v_mfma_f32_16x16x32_bf16 v[100:103], v[158:161], v[196:199], v[100:103]
	v_mfma_f32_16x16x32_bf16 v[84:87], v[158:161], v[204:207], v[84:87]
	v_mfma_f32_16x16x32_bf16 v[80:83], v[166:169], v[204:207], v[80:83]
	v_mfma_f32_16x16x32_bf16 v[48:51], v[166:169], v[212:215], v[48:51]
	v_mfma_f32_16x16x32_bf16 v[52:55], v[158:161], v[212:215], v[52:55]
	s_setprio 0
	s_barrier
	ds_read_b128 v[170:173], v180 offset:49152
	ds_read_b128 v[188:191], v180 offset:50176
	ds_read_b128 v[192:195], v180 offset:51200
	ds_read_b128 v[196:199], v180 offset:52224
	ds_read_b128 v[200:203], v180 offset:53248
	ds_read_b128 v[204:207], v180 offset:54272
	ds_read_b128 v[208:211], v180 offset:55296
	ds_read_b128 v[212:215], v180 offset:56320
	s_add_u32 s40, s42, 0x80
	s_addc_u32 s41, s43, 0
	s_mov_b32 s48, m0
	s_mov_b32 m0, s33
	s_nop 0
	global_load_lds_dwordx4 v147, s[40:41]
	s_mov_b32 m0, s48
	s_nop 0
	s_mov_b32 s48, m0
	s_mov_b32 m0, s63
	s_nop 0
	global_load_lds_dwordx4 v149, s[40:41]
	s_mov_b32 m0, s48
	s_add_u32 s40, s42, 0x40080
	s_addc_u32 s41, s43, 0
	s_mov_b32 s42, m0
	s_mov_b32 m0, s70
	s_nop 0
	global_load_lds_dwordx4 v147, s[40:41]
	s_mov_b32 m0, s42
	s_nop 0
	s_mov_b32 s42, m0
	s_mov_b32 m0, s71
	s_nop 0
	global_load_lds_dwordx4 v149, s[40:41]
	s_mov_b32 m0, s42
	s_mov_b32 s40, m0
	s_mov_b32 m0, s68
	s_nop 0
	global_load_lds_dwordx4 v151, s[38:39]
	s_mov_b32 m0, s40
	s_nop 0
	s_mov_b32 s40, m0
	s_mov_b32 m0, s69
	s_nop 0
	global_load_lds_dwordx4 v174, s[38:39]
	s_mov_b32 m0, s40
	s_waitcnt vmcnt(8)
	s_waitcnt lgkmcnt(0)
	s_barrier
	s_setprio 1
	s_waitcnt lgkmcnt(7)
	v_mfma_f32_16x16x32_bf16 v[76:79], v[128:131], v[170:173], v[76:79]
	v_mfma_f32_16x16x32_bf16 v[72:75], v[136:139], v[170:173], v[72:75]
	s_waitcnt lgkmcnt(5)
	v_mfma_f32_16x16x32_bf16 v[40:43], v[136:139], v[192:195], v[40:43]
	v_mfma_f32_16x16x32_bf16 v[44:47], v[128:131], v[192:195], v[44:47]
	s_waitcnt lgkmcnt(3)
	v_mfma_f32_16x16x32_bf16 v[28:31], v[128:131], v[200:203], v[28:31]
	v_mfma_f32_16x16x32_bf16 v[24:27], v[136:139], v[200:203], v[24:27]
	s_waitcnt lgkmcnt(1)
	v_mfma_f32_16x16x32_bf16 v[8:11], v[136:139], v[208:211], v[8:11]
	v_mfma_f32_16x16x32_bf16 v[12:15], v[128:131], v[208:211], v[12:15]
	v_mfma_f32_16x16x32_bf16 v[76:79], v[132:135], v[188:191], v[76:79]
	v_mfma_f32_16x16x32_bf16 v[72:75], v[140:143], v[188:191], v[72:75]
	v_mfma_f32_16x16x32_bf16 v[40:43], v[140:143], v[196:199], v[40:43]
	v_mfma_f32_16x16x32_bf16 v[44:47], v[132:135], v[196:199], v[44:47]
	v_mfma_f32_16x16x32_bf16 v[28:31], v[132:135], v[204:207], v[28:31]
	v_mfma_f32_16x16x32_bf16 v[24:27], v[140:143], v[204:207], v[24:27]
	s_waitcnt lgkmcnt(0)
	v_mfma_f32_16x16x32_bf16 v[8:11], v[140:143], v[212:215], v[8:11]
	v_mfma_f32_16x16x32_bf16 v[12:15], v[132:135], v[212:215], v[12:15]
	s_setprio 0
	s_setprio 1
	v_mfma_f32_16x16x32_bf16 v[68:71], v[152:155], v[170:173], v[68:71]
	v_mfma_f32_16x16x32_bf16 v[64:67], v[162:165], v[170:173], v[64:67]
	v_mfma_f32_16x16x32_bf16 v[32:35], v[162:165], v[192:195], v[32:35]
	v_mfma_f32_16x16x32_bf16 v[36:39], v[152:155], v[192:195], v[36:39]
	v_mfma_f32_16x16x32_bf16 v[20:23], v[152:155], v[200:203], v[20:23]
	v_mfma_f32_16x16x32_bf16 v[16:19], v[162:165], v[200:203], v[16:19]
	v_mfma_f32_16x16x32_bf16 v[0:3], v[162:165], v[208:211], v[0:3]
	v_mfma_f32_16x16x32_bf16 v[4:7], v[152:155], v[208:211], v[4:7]
	v_mfma_f32_16x16x32_bf16 v[68:71], v[158:161], v[188:191], v[68:71]
	v_mfma_f32_16x16x32_bf16 v[64:67], v[166:169], v[188:191], v[64:67]
	v_mfma_f32_16x16x32_bf16 v[32:35], v[166:169], v[196:199], v[32:35]
	v_mfma_f32_16x16x32_bf16 v[36:39], v[158:161], v[196:199], v[36:39]
	v_mfma_f32_16x16x32_bf16 v[20:23], v[158:161], v[204:207], v[20:23]
	v_mfma_f32_16x16x32_bf16 v[16:19], v[166:169], v[204:207], v[16:19]
	v_mfma_f32_16x16x32_bf16 v[0:3], v[166:169], v[212:215], v[0:3]
	v_mfma_f32_16x16x32_bf16 v[4:7], v[158:161], v[212:215], v[4:7]
	s_setprio 0
	s_barrier
	s_add_i32 s90, s90, 2
	s_add_u32 s87, s87, 0x100
	s_addc_u32 s89, s89, 0
	s_cmp_gt_u32 s90, 13
	s_mov_b64 s[40:41], s[36:37]
	s_cbranch_scc0 .LBB0_784
	s_and_b64 vcc, exec, s[22:23]
	s_cbranch_vccz .LBB0_787
	s_barrier

.LBB0_1129:
	ds_read_b128 v[80:83], v199
	ds_read_b128 v[84:87], v199 offset:1024
	ds_read_b128 v[104:107], v199 offset:2048
	ds_read_b128 v[108:111], v199 offset:3072
	ds_read_b128 v[128:131], v200
	ds_read_b128 v[132:135], v200 offset:1024
	ds_read_b128 v[152:155], v200 offset:2048
	ds_read_b128 v[156:159], v200 offset:3072
	s_add_u32 s40, s42, 0x100
	s_addc_u32 s41, s43, 0
	s_cmp_eq_u32 s86, 12
	s_cselect_b32 s52, s29, s40
	s_cselect_b32 s53, s9, s41
	s_cselect_b32 s50, s83, s84
	s_cselect_b32 s51, s31, s85
	s_add_u32 s48, s52, 0x80
	s_addc_u32 s49, s53, 0
	ds_read_b128 v[160:163], v201
	ds_read_b128 v[164:167], v201 offset:1024
	ds_read_b128 v[168:171], v201 offset:2048
	ds_read_b128 v[172:175], v201 offset:3072
	ds_read_b128 v[176:179], v201 offset:4096
	ds_read_b128 v[180:183], v201 offset:5120
	ds_read_b128 v[190:193], v201 offset:6144
	ds_read_b128 v[206:209], v201 offset:7168
	s_add_u32 s42, s42, 0x40080
	s_addc_u32 s43, s43, 0
	s_mov_b32 s58, m0
	s_mov_b32 m0, s70
	s_nop 0
	global_load_lds_dwordx4 v195, s[42:43]
	s_mov_b32 m0, s58
	s_nop 0
	s_mov_b32 s58, m0
	s_mov_b32 m0, s73
	s_nop 0
	global_load_lds_dwordx4 v196, s[42:43]
	s_mov_b32 m0, s58
	s_waitcnt vmcnt(8)
	s_waitcnt lgkmcnt(0)
	s_barrier
	s_setprio 1
	s_waitcnt lgkmcnt(7)
	v_mfma_f32_16x16x32_bf16 v[136:139], v[80:83], v[160:163], v[136:139]
	v_mfma_f32_16x16x32_bf16 v[140:143], v[104:107], v[160:163], v[140:143]
	s_waitcnt lgkmcnt(5)
	v_mfma_f32_16x16x32_bf16 v[120:123], v[104:107], v[168:171], v[120:123]
	v_mfma_f32_16x16x32_bf16 v[124:127], v[80:83], v[168:171], v[124:127]
	s_waitcnt lgkmcnt(3)
	v_mfma_f32_16x16x32_bf16 v[100:103], v[80:83], v[176:179], v[100:103]
	v_mfma_f32_16x16x32_bf16 v[96:99], v[104:107], v[176:179], v[96:99]
	s_waitcnt lgkmcnt(1)
	v_mfma_f32_16x16x32_bf16 v[72:75], v[104:107], v[190:193], v[72:75]
	v_mfma_f32_16x16x32_bf16 v[76:79], v[80:83], v[190:193], v[76:79]
	v_mfma_f32_16x16x32_bf16 v[136:139], v[84:87], v[164:167], v[136:139]
	v_mfma_f32_16x16x32_bf16 v[140:143], v[108:111], v[164:167], v[140:143]
	v_mfma_f32_16x16x32_bf16 v[120:123], v[108:111], v[172:175], v[120:123]
	v_mfma_f32_16x16x32_bf16 v[124:127], v[84:87], v[172:175], v[124:127]
	v_mfma_f32_16x16x32_bf16 v[100:103], v[84:87], v[180:183], v[100:103]
	v_mfma_f32_16x16x32_bf16 v[96:99], v[108:111], v[180:183], v[96:99]
	s_waitcnt lgkmcnt(0)
	v_mfma_f32_16x16x32_bf16 v[72:75], v[108:111], v[206:209], v[72:75]
	v_mfma_f32_16x16x32_bf16 v[76:79], v[84:87], v[206:209], v[76:79]
	s_setprio 0
	s_setprio 1
	v_mfma_f32_16x16x32_bf16 v[148:151], v[128:131], v[160:163], v[148:151]
	v_mfma_f32_16x16x32_bf16 v[144:147], v[152:155], v[160:163], v[144:147]
	v_mfma_f32_16x16x32_bf16 v[112:115], v[152:155], v[168:171], v[112:115]
	v_mfma_f32_16x16x32_bf16 v[116:119], v[128:131], v[168:171], v[116:119]
	v_mfma_f32_16x16x32_bf16 v[92:95], v[128:131], v[176:179], v[92:95]
	v_mfma_f32_16x16x32_bf16 v[88:91], v[152:155], v[176:179], v[88:91]
	v_mfma_f32_16x16x32_bf16 v[64:67], v[152:155], v[190:193], v[64:67]
	v_mfma_f32_16x16x32_bf16 v[68:71], v[128:131], v[190:193], v[68:71]
	v_mfma_f32_16x16x32_bf16 v[148:151], v[132:135], v[164:167], v[148:151]
	v_mfma_f32_16x16x32_bf16 v[144:147], v[156:159], v[164:167], v[144:147]
	v_mfma_f32_16x16x32_bf16 v[112:115], v[156:159], v[172:175], v[112:115]
	v_mfma_f32_16x16x32_bf16 v[116:119], v[132:135], v[172:175], v[116:119]
	v_mfma_f32_16x16x32_bf16 v[92:95], v[132:135], v[180:183], v[92:95]
	v_mfma_f32_16x16x32_bf16 v[88:91], v[156:159], v[180:183], v[88:91]
	v_mfma_f32_16x16x32_bf16 v[64:67], v[156:159], v[206:209], v[64:67]
	v_mfma_f32_16x16x32_bf16 v[68:71], v[132:135], v[206:209], v[68:71]
	s_setprio 0
	s_barrier
	ds_read_b128 v[160:163], v201 offset:16384
	ds_read_b128 v[164:167], v201 offset:17408
	ds_read_b128 v[168:171], v201 offset:18432
	ds_read_b128 v[172:175], v201 offset:19456
	ds_read_b128 v[176:179], v201 offset:20480
	ds_read_b128 v[180:183], v201 offset:21504
	ds_read_b128 v[190:193], v201 offset:22528
	ds_read_b128 v[206:209], v201 offset:23552
	s_mov_b32 s42, m0
	s_mov_b32 m0, s71
	s_nop 0
	global_load_lds_dwordx4 v185, s[50:51]
	s_mov_b32 m0, s42
	s_nop 0
	s_mov_b32 s42, m0
	s_mov_b32 m0, s76
	s_nop 0
	global_load_lds_dwordx4 v194, s[50:51]
	s_mov_b32 m0, s42
	s_add_u32 s42, s50, 0x40000
	s_addc_u32 s43, s51, 0
	s_mov_b32 s58, m0
	s_mov_b32 m0, s72
	s_nop 0
	global_load_lds_dwordx4 v185, s[42:43]
	s_mov_b32 m0, s58
	s_nop 0
	s_mov_b32 s58, m0
	s_mov_b32 m0, s77
	s_nop 0
	global_load_lds_dwordx4 v194, s[42:43]
	s_mov_b32 m0, s58
	s_mov_b32 s42, m0
	s_mov_b32 m0, s4
	s_nop 0
	global_load_lds_dwordx4 v195, s[52:53]
	s_mov_b32 m0, s42
	s_nop 0
	s_mov_b32 s42, m0
	s_mov_b32 m0, s5
	s_nop 0
	global_load_lds_dwordx4 v196, s[52:53]
	s_mov_b32 m0, s42
	s_waitcnt vmcnt(8)
	s_waitcnt lgkmcnt(0)
	s_barrier
	s_setprio 1
	s_waitcnt lgkmcnt(7)
	v_mfma_f32_16x16x32_bf16 v[60:63], v[80:83], v[160:163], v[60:63]
	v_mfma_f32_16x16x32_bf16 v[56:59], v[104:107], v[160:163], v[56:59]
	s_waitcnt lgkmcnt(5)
	v_mfma_f32_16x16x32_bf16 v[40:43], v[104:107], v[168:171], v[40:43]
	v_mfma_f32_16x16x32_bf16 v[44:47], v[80:83], v[168:171], v[44:47]
	s_waitcnt lgkmcnt(3)
	v_mfma_f32_16x16x32_bf16 v[28:31], v[80:83], v[176:179], v[28:31]
	v_mfma_f32_16x16x32_bf16 v[24:27], v[104:107], v[176:179], v[24:27]
	s_waitcnt lgkmcnt(1)
	v_mfma_f32_16x16x32_bf16 v[8:11], v[104:107], v[190:193], v[8:11]
	v_mfma_f32_16x16x32_bf16 v[12:15], v[80:83], v[190:193], v[12:15]
	v_mfma_f32_16x16x32_bf16 v[60:63], v[84:87], v[164:167], v[60:63]
	v_mfma_f32_16x16x32_bf16 v[56:59], v[108:111], v[164:167], v[56:59]
	v_mfma_f32_16x16x32_bf16 v[40:43], v[108:111], v[172:175], v[40:43]
	v_mfma_f32_16x16x32_bf16 v[44:47], v[84:87], v[172:175], v[44:47]
	v_mfma_f32_16x16x32_bf16 v[28:31], v[84:87], v[180:183], v[28:31]
	v_mfma_f32_16x16x32_bf16 v[24:27], v[108:111], v[180:183], v[24:27]
	s_waitcnt lgkmcnt(0)
	v_mfma_f32_16x16x32_bf16 v[8:11], v[108:111], v[206:209], v[8:11]
	v_mfma_f32_16x16x32_bf16 v[12:15], v[84:87], v[206:209], v[12:15]
	s_setprio 0
	s_setprio 1
	v_mfma_f32_16x16x32_bf16 v[52:55], v[128:131], v[160:163], v[52:55]
	v_mfma_f32_16x16x32_bf16 v[48:51], v[152:155], v[160:163], v[48:51]
	v_mfma_f32_16x16x32_bf16 v[32:35], v[152:155], v[168:171], v[32:35]
	v_mfma_f32_16x16x32_bf16 v[36:39], v[128:131], v[168:171], v[36:39]
	v_mfma_f32_16x16x32_bf16 v[20:23], v[128:131], v[176:179], v[20:23]
	v_mfma_f32_16x16x32_bf16 v[16:19], v[152:155], v[176:179], v[16:19]
	v_mfma_f32_16x16x32_bf16 v[0:3], v[152:155], v[190:193], v[0:3]
	v_mfma_f32_16x16x32_bf16 v[4:7], v[128:131], v[190:193], v[4:7]
	v_mfma_f32_16x16x32_bf16 v[52:55], v[132:135], v[164:167], v[52:55]
	v_mfma_f32_16x16x32_bf16 v[48:51], v[156:159], v[164:167], v[48:51]
	v_mfma_f32_16x16x32_bf16 v[32:35], v[156:159], v[172:175], v[32:35]
	v_mfma_f32_16x16x32_bf16 v[36:39], v[132:135], v[172:175], v[36:39]
	v_mfma_f32_16x16x32_bf16 v[20:23], v[132:135], v[180:183], v[20:23]
	v_mfma_f32_16x16x32_bf16 v[16:19], v[156:159], v[180:183], v[16:19]
	v_mfma_f32_16x16x32_bf16 v[0:3], v[156:159], v[206:209], v[0:3]
	v_mfma_f32_16x16x32_bf16 v[4:7], v[132:135], v[206:209], v[4:7]
	s_setprio 0
	s_barrier
	ds_read_b128 v[80:83], v202
	ds_read_b128 v[84:87], v202 offset:1024
	ds_read_b128 v[104:107], v202 offset:2048
	ds_read_b128 v[108:111], v202 offset:3072
	ds_read_b128 v[128:131], v203
	ds_read_b128 v[132:135], v203 offset:1024
	ds_read_b128 v[152:155], v203 offset:2048
	ds_read_b128 v[156:159], v203 offset:3072
	ds_read_b128 v[160:163], v201 offset:32768
	ds_read_b128 v[164:167], v201 offset:33792
	ds_read_b128 v[168:171], v201 offset:34816
	ds_read_b128 v[172:175], v201 offset:35840
	ds_read_b128 v[176:179], v201 offset:36864
	ds_read_b128 v[180:183], v201 offset:37888
	ds_read_b128 v[190:193], v201 offset:38912
	ds_read_b128 v[206:209], v201 offset:39936
	s_add_u32 s42, s52, 0x40000
	s_addc_u32 s43, s53, 0
	s_mov_b32 s52, m0
	s_mov_b32 m0, s33
	s_nop 0
	global_load_lds_dwordx4 v195, s[42:43]
	s_mov_b32 m0, s52
	s_nop 0
	s_mov_b32 s52, m0
	s_mov_b32 m0, s39
	s_nop 0
	global_load_lds_dwordx4 v196, s[42:43]
	s_mov_b32 m0, s52
	s_waitcnt vmcnt(8)
	s_waitcnt lgkmcnt(0)
	s_barrier
	s_setprio 1
	s_waitcnt lgkmcnt(7)
	v_mfma_f32_16x16x32_bf16 v[136:139], v[80:83], v[160:163], v[136:139]
	v_mfma_f32_16x16x32_bf16 v[140:143], v[104:107], v[160:163], v[140:143]
	s_waitcnt lgkmcnt(5)
	v_mfma_f32_16x16x32_bf16 v[120:123], v[104:107], v[168:171], v[120:123]
	v_mfma_f32_16x16x32_bf16 v[124:127], v[80:83], v[168:171], v[124:127]
	s_waitcnt lgkmcnt(3)
	v_mfma_f32_16x16x32_bf16 v[100:103], v[80:83], v[176:179], v[100:103]
	v_mfma_f32_16x16x32_bf16 v[96:99], v[104:107], v[176:179], v[96:99]
	s_waitcnt lgkmcnt(1)
	v_mfma_f32_16x16x32_bf16 v[72:75], v[104:107], v[190:193], v[72:75]
	v_mfma_f32_16x16x32_bf16 v[76:79], v[80:83], v[190:193], v[76:79]
	v_mfma_f32_16x16x32_bf16 v[136:139], v[84:87], v[164:167], v[136:139]
	v_mfma_f32_16x16x32_bf16 v[140:143], v[108:111], v[164:167], v[140:143]
	v_mfma_f32_16x16x32_bf16 v[120:123], v[108:111], v[172:175], v[120:123]
	v_mfma_f32_16x16x32_bf16 v[124:127], v[84:87], v[172:175], v[124:127]
	v_mfma_f32_16x16x32_bf16 v[100:103], v[84:87], v[180:183], v[100:103]
	v_mfma_f32_16x16x32_bf16 v[96:99], v[108:111], v[180:183], v[96:99]
	s_waitcnt lgkmcnt(0)
	v_mfma_f32_16x16x32_bf16 v[72:75], v[108:111], v[206:209], v[72:75]
	v_mfma_f32_16x16x32_bf16 v[76:79], v[84:87], v[206:209], v[76:79]
	s_setprio 0
	s_setprio 1
	v_mfma_f32_16x16x32_bf16 v[148:151], v[128:131], v[160:163], v[148:151]
	v_mfma_f32_16x16x32_bf16 v[144:147], v[152:155], v[160:163], v[144:147]
	v_mfma_f32_16x16x32_bf16 v[112:115], v[152:155], v[168:171], v[112:115]
	v_mfma_f32_16x16x32_bf16 v[116:119], v[128:131], v[168:171], v[116:119]
	v_mfma_f32_16x16x32_bf16 v[92:95], v[128:131], v[176:179], v[92:95]
	v_mfma_f32_16x16x32_bf16 v[88:91], v[152:155], v[176:179], v[88:91]
	v_mfma_f32_16x16x32_bf16 v[64:67], v[152:155], v[190:193], v[64:67]
	v_mfma_f32_16x16x32_bf16 v[68:71], v[128:131], v[190:193], v[68:71]
	v_mfma_f32_16x16x32_bf16 v[148:151], v[132:135], v[164:167], v[148:151]
	v_mfma_f32_16x16x32_bf16 v[144:147], v[156:159], v[164:167], v[144:147]
	v_mfma_f32_16x16x32_bf16 v[112:115], v[156:159], v[172:175], v[112:115]
	v_mfma_f32_16x16x32_bf16 v[116:119], v[132:135], v[172:175], v[116:119]
	v_mfma_f32_16x16x32_bf16 v[92:95], v[132:135], v[180:183], v[92:95]
	v_mfma_f32_16x16x32_bf16 v[88:91], v[156:159], v[180:183], v[88:91]
	v_mfma_f32_16x16x32_bf16 v[64:67], v[156:159], v[206:209], v[64:67]
	v_mfma_f32_16x16x32_bf16 v[68:71], v[132:135], v[206:209], v[68:71]
	s_setprio 0
	s_barrier
	ds_read_b128 v[160:163], v201 offset:49152
	ds_read_b128 v[164:167], v201 offset:50176
	ds_read_b128 v[168:171], v201 offset:51200
	ds_read_b128 v[172:175], v201 offset:52224
	ds_read_b128 v[176:179], v201 offset:53248
	ds_read_b128 v[180:183], v201 offset:54272
	ds_read_b128 v[190:193], v201 offset:55296
	ds_read_b128 v[206:209], v201 offset:56320
	s_add_u32 s42, s50, 0x80
	s_addc_u32 s43, s51, 0
	s_mov_b32 s52, m0
	s_mov_b32 m0, s54
	s_nop 0
	global_load_lds_dwordx4 v185, s[42:43]
	s_mov_b32 m0, s52
	s_nop 0
	s_mov_b32 s52, m0
	s_mov_b32 m0, s55
	s_nop 0
	global_load_lds_dwordx4 v194, s[42:43]
	s_mov_b32 m0, s52
	s_add_u32 s42, s50, 0x40080
	s_addc_u32 s43, s51, 0
	s_mov_b32 s50, m0
	s_mov_b32 m0, s68
	s_nop 0
	global_load_lds_dwordx4 v185, s[42:43]
	s_mov_b32 m0, s50
	s_nop 0
	s_mov_b32 s50, m0
	s_mov_b32 m0, s69
	s_nop 0
	global_load_lds_dwordx4 v194, s[42:43]
	s_mov_b32 m0, s50
	s_mov_b32 s42, m0
	s_mov_b32 m0, s62
	s_nop 0
	global_load_lds_dwordx4 v195, s[48:49]
	s_mov_b32 m0, s42
	s_nop 0
	s_mov_b32 s42, m0
	s_mov_b32 m0, s63
	s_nop 0
	global_load_lds_dwordx4 v196, s[48:49]
	s_mov_b32 m0, s42
	s_waitcnt vmcnt(8)
	s_waitcnt lgkmcnt(0)
	s_barrier
	s_setprio 1
	s_waitcnt lgkmcnt(7)
	v_mfma_f32_16x16x32_bf16 v[60:63], v[80:83], v[160:163], v[60:63]
	v_mfma_f32_16x16x32_bf16 v[56:59], v[104:107], v[160:163], v[56:59]
	s_waitcnt lgkmcnt(5)
	v_mfma_f32_16x16x32_bf16 v[40:43], v[104:107], v[168:171], v[40:43]
	v_mfma_f32_16x16x32_bf16 v[44:47], v[80:83], v[168:171], v[44:47]
	s_waitcnt lgkmcnt(3)
	v_mfma_f32_16x16x32_bf16 v[28:31], v[80:83], v[176:179], v[28:31]
	v_mfma_f32_16x16x32_bf16 v[24:27], v[104:107], v[176:179], v[24:27]
	s_waitcnt lgkmcnt(1)
	v_mfma_f32_16x16x32_bf16 v[8:11], v[104:107], v[190:193], v[8:11]
	v_mfma_f32_16x16x32_bf16 v[12:15], v[80:83], v[190:193], v[12:15]
	v_mfma_f32_16x16x32_bf16 v[60:63], v[84:87], v[164:167], v[60:63]
	v_mfma_f32_16x16x32_bf16 v[56:59], v[108:111], v[164:167], v[56:59]
	v_mfma_f32_16x16x32_bf16 v[40:43], v[108:111], v[172:175], v[40:43]
	v_mfma_f32_16x16x32_bf16 v[44:47], v[84:87], v[172:175], v[44:47]
	v_mfma_f32_16x16x32_bf16 v[28:31], v[84:87], v[180:183], v[28:31]
	v_mfma_f32_16x16x32_bf16 v[24:27], v[108:111], v[180:183], v[24:27]
	s_waitcnt lgkmcnt(0)
	v_mfma_f32_16x16x32_bf16 v[8:11], v[108:111], v[206:209], v[8:11]
	v_mfma_f32_16x16x32_bf16 v[12:15], v[84:87], v[206:209], v[12:15]
	s_setprio 0
	s_setprio 1
	v_mfma_f32_16x16x32_bf16 v[52:55], v[128:131], v[160:163], v[52:55]
	v_mfma_f32_16x16x32_bf16 v[48:51], v[152:155], v[160:163], v[48:51]
	v_mfma_f32_16x16x32_bf16 v[32:35], v[152:155], v[168:171], v[32:35]
	v_mfma_f32_16x16x32_bf16 v[36:39], v[128:131], v[168:171], v[36:39]
	v_mfma_f32_16x16x32_bf16 v[20:23], v[128:131], v[176:179], v[20:23]
	v_mfma_f32_16x16x32_bf16 v[16:19], v[152:155], v[176:179], v[16:19]
	v_mfma_f32_16x16x32_bf16 v[0:3], v[152:155], v[190:193], v[0:3]
	v_mfma_f32_16x16x32_bf16 v[4:7], v[128:131], v[190:193], v[4:7]
	v_mfma_f32_16x16x32_bf16 v[52:55], v[132:135], v[164:167], v[52:55]
	v_mfma_f32_16x16x32_bf16 v[48:51], v[156:159], v[164:167], v[48:51]
	v_mfma_f32_16x16x32_bf16 v[32:35], v[156:159], v[172:175], v[32:35]
	v_mfma_f32_16x16x32_bf16 v[36:39], v[132:135], v[172:175], v[36:39]
	v_mfma_f32_16x16x32_bf16 v[20:23], v[132:135], v[180:183], v[20:23]
	v_mfma_f32_16x16x32_bf16 v[16:19], v[156:159], v[180:183], v[16:19]
	v_mfma_f32_16x16x32_bf16 v[0:3], v[156:159], v[206:209], v[0:3]
	v_mfma_f32_16x16x32_bf16 v[4:7], v[132:135], v[206:209], v[4:7]
	s_setprio 0
	s_barrier
	s_add_i32 s86, s86, 2
	s_add_u32 s84, s84, 0x100
	s_addc_u32 s85, s85, 0
	s_cmp_gt_u32 s86, 13
	s_mov_b64 s[42:43], s[40:41]
	s_cbranch_scc0 .LBB0_1129
	s_and_b64 vcc, exec, s[18:19]
	s_cbranch_vccz .LBB0_1132
	s_barrier

.LBB0_1254:
	ds_read_b128 v[132:135], v147
	ds_read_b128 v[136:139], v147 offset:1024
	ds_read_b128 v[152:155], v147 offset:2048
	ds_read_b128 v[156:159], v147 offset:3072
	ds_read_b128 v[160:163], v148
	ds_read_b128 v[164:167], v148 offset:1024
	ds_read_b128 v[168:171], v148 offset:2048
	ds_read_b128 v[172:175], v148 offset:3072
	s_add_u32 s24, s28, 0x100
	s_addc_u32 s25, s29, 0
	s_cmp_eq_u32 s79, 12
	s_cselect_b32 s34, s17, s24
	s_cselect_b32 s35, s13, s25
	s_cselect_b32 s30, s76, s77
	s_cselect_b32 s31, s75, s78
	s_add_u32 s26, s34, 0x80
	s_addc_u32 s27, s35, 0
	ds_read_b128 v[176:179], v149
	ds_read_b128 v[180:183], v149 offset:1024
	ds_read_b128 v[186:189], v149 offset:2048
	ds_read_b128 v[190:193], v149 offset:3072
	ds_read_b128 v[194:197], v149 offset:4096
	ds_read_b128 v[198:201], v149 offset:5120
	ds_read_b128 v[202:205], v149 offset:6144
	ds_read_b128 v[206:209], v149 offset:7168
	s_add_u32 s28, s28, 0x40080
	s_addc_u32 s29, s29, 0
	s_mov_b32 s58, m0
	s_mov_b32 m0, s50
	s_nop 0
	global_load_lds_dwordx4 v142, s[28:29]
	s_mov_b32 m0, s58
	s_nop 0
	s_mov_b32 s58, m0
	s_mov_b32 m0, s53
	s_nop 0
	global_load_lds_dwordx4 v143, s[28:29]
	s_mov_b32 m0, s58
	s_waitcnt vmcnt(8)
	s_waitcnt lgkmcnt(0)
	s_barrier
	s_setprio 1
	s_waitcnt lgkmcnt(7)
	v_mfma_f32_16x16x32_bf16 v[120:123], v[132:135], v[176:179], v[120:123]
	v_mfma_f32_16x16x32_bf16 v[112:115], v[152:155], v[176:179], v[112:115]
	s_waitcnt lgkmcnt(5)
	v_mfma_f32_16x16x32_bf16 v[96:99], v[152:155], v[186:189], v[96:99]
	v_mfma_f32_16x16x32_bf16 v[104:107], v[132:135], v[186:189], v[104:107]
	s_waitcnt lgkmcnt(3)
	v_mfma_f32_16x16x32_bf16 v[88:91], v[132:135], v[194:197], v[88:91]
	v_mfma_f32_16x16x32_bf16 v[80:83], v[152:155], v[194:197], v[80:83]
	s_waitcnt lgkmcnt(1)
	v_mfma_f32_16x16x32_bf16 v[56:59], v[152:155], v[202:205], v[56:59]
	v_mfma_f32_16x16x32_bf16 v[72:75], v[132:135], v[202:205], v[72:75]
	v_mfma_f32_16x16x32_bf16 v[120:123], v[136:139], v[180:183], v[120:123]
	v_mfma_f32_16x16x32_bf16 v[112:115], v[156:159], v[180:183], v[112:115]
	v_mfma_f32_16x16x32_bf16 v[96:99], v[156:159], v[190:193], v[96:99]
	v_mfma_f32_16x16x32_bf16 v[104:107], v[136:139], v[190:193], v[104:107]
	v_mfma_f32_16x16x32_bf16 v[88:91], v[136:139], v[198:201], v[88:91]
	v_mfma_f32_16x16x32_bf16 v[80:83], v[156:159], v[198:201], v[80:83]
	s_waitcnt lgkmcnt(0)
	v_mfma_f32_16x16x32_bf16 v[56:59], v[156:159], v[206:209], v[56:59]
	v_mfma_f32_16x16x32_bf16 v[72:75], v[136:139], v[206:209], v[72:75]
	s_setprio 0
	s_setprio 1
	v_mfma_f32_16x16x32_bf16 v[124:127], v[160:163], v[176:179], v[124:127]
	v_mfma_f32_16x16x32_bf16 v[116:119], v[168:171], v[176:179], v[116:119]
	v_mfma_f32_16x16x32_bf16 v[100:103], v[168:171], v[186:189], v[100:103]
	v_mfma_f32_16x16x32_bf16 v[108:111], v[160:163], v[186:189], v[108:111]
	v_mfma_f32_16x16x32_bf16 v[92:95], v[160:163], v[194:197], v[92:95]
	v_mfma_f32_16x16x32_bf16 v[84:87], v[168:171], v[194:197], v[84:87]
	v_mfma_f32_16x16x32_bf16 v[64:67], v[168:171], v[202:205], v[64:67]
	v_mfma_f32_16x16x32_bf16 v[76:79], v[160:163], v[202:205], v[76:79]
	v_mfma_f32_16x16x32_bf16 v[124:127], v[164:167], v[180:183], v[124:127]
	v_mfma_f32_16x16x32_bf16 v[116:119], v[172:175], v[180:183], v[116:119]
	v_mfma_f32_16x16x32_bf16 v[100:103], v[172:175], v[190:193], v[100:103]
	v_mfma_f32_16x16x32_bf16 v[108:111], v[164:167], v[190:193], v[108:111]
	v_mfma_f32_16x16x32_bf16 v[92:95], v[164:167], v[198:201], v[92:95]
	v_mfma_f32_16x16x32_bf16 v[84:87], v[172:175], v[198:201], v[84:87]
	v_mfma_f32_16x16x32_bf16 v[64:67], v[172:175], v[206:209], v[64:67]
	v_mfma_f32_16x16x32_bf16 v[76:79], v[164:167], v[206:209], v[76:79]
	s_setprio 0
	s_barrier
	ds_read_b128 v[176:179], v149 offset:16384
	ds_read_b128 v[180:183], v149 offset:17408
	ds_read_b128 v[186:189], v149 offset:18432
	ds_read_b128 v[190:193], v149 offset:19456
	ds_read_b128 v[194:197], v149 offset:20480
	ds_read_b128 v[198:201], v149 offset:21504
	ds_read_b128 v[202:205], v149 offset:22528
	ds_read_b128 v[206:209], v149 offset:23552
	s_mov_b32 s28, m0
	s_mov_b32 m0, s51
	s_nop 0
	global_load_lds_dwordx4 v140, s[30:31]
	s_mov_b32 m0, s28
	s_nop 0
	s_mov_b32 s28, m0
	s_mov_b32 m0, s54
	s_nop 0
	global_load_lds_dwordx4 v141, s[30:31]
	s_mov_b32 m0, s28
	s_add_u32 s28, s30, 0x40000
	s_addc_u32 s29, s31, 0
	s_mov_b32 s58, m0
	s_mov_b32 m0, s52
	s_nop 0
	global_load_lds_dwordx4 v140, s[28:29]
	s_mov_b32 m0, s58
	s_nop 0
	s_mov_b32 s58, m0
	s_mov_b32 m0, s62
	s_nop 0
	global_load_lds_dwordx4 v141, s[28:29]
	s_mov_b32 m0, s58
	s_mov_b32 s28, m0
	s_mov_b32 m0, s23
	s_nop 0
	global_load_lds_dwordx4 v142, s[34:35]
	s_mov_b32 m0, s28
	s_nop 0
	s_mov_b32 s28, m0
	s_mov_b32 m0, s36
	s_nop 0
	global_load_lds_dwordx4 v143, s[34:35]
	s_mov_b32 m0, s28
	s_waitcnt vmcnt(8)
	s_waitcnt lgkmcnt(0)
	s_barrier
	s_setprio 1
	s_waitcnt lgkmcnt(7)
	v_mfma_f32_16x16x32_bf16 v[60:63], v[132:135], v[176:179], v[60:63]
	v_mfma_f32_16x16x32_bf16 v[48:51], v[152:155], v[176:179], v[48:51]
	s_waitcnt lgkmcnt(5)
	v_mfma_f32_16x16x32_bf16 v[32:35], v[152:155], v[186:189], v[32:35]
	v_mfma_f32_16x16x32_bf16 v[40:43], v[132:135], v[186:189], v[40:43]
	s_waitcnt lgkmcnt(3)
	v_mfma_f32_16x16x32_bf16 v[24:27], v[132:135], v[194:197], v[24:27]
	v_mfma_f32_16x16x32_bf16 v[16:19], v[152:155], v[194:197], v[16:19]
	s_waitcnt lgkmcnt(1)
	v_mfma_f32_16x16x32_bf16 v[0:3], v[152:155], v[202:205], v[0:3]
	v_mfma_f32_16x16x32_bf16 v[8:11], v[132:135], v[202:205], v[8:11]
	v_mfma_f32_16x16x32_bf16 v[60:63], v[136:139], v[180:183], v[60:63]
	v_mfma_f32_16x16x32_bf16 v[48:51], v[156:159], v[180:183], v[48:51]
	v_mfma_f32_16x16x32_bf16 v[32:35], v[156:159], v[190:193], v[32:35]
	v_mfma_f32_16x16x32_bf16 v[40:43], v[136:139], v[190:193], v[40:43]
	v_mfma_f32_16x16x32_bf16 v[24:27], v[136:139], v[198:201], v[24:27]
	v_mfma_f32_16x16x32_bf16 v[16:19], v[156:159], v[198:201], v[16:19]
	s_waitcnt lgkmcnt(0)
	v_mfma_f32_16x16x32_bf16 v[0:3], v[156:159], v[206:209], v[0:3]
	v_mfma_f32_16x16x32_bf16 v[8:11], v[136:139], v[206:209], v[8:11]
	s_setprio 0
	s_setprio 1
	v_mfma_f32_16x16x32_bf16 v[68:71], v[160:163], v[176:179], v[68:71]
	v_mfma_f32_16x16x32_bf16 v[52:55], v[168:171], v[176:179], v[52:55]
	v_mfma_f32_16x16x32_bf16 v[36:39], v[168:171], v[186:189], v[36:39]
	v_mfma_f32_16x16x32_bf16 v[44:47], v[160:163], v[186:189], v[44:47]
	v_mfma_f32_16x16x32_bf16 v[28:31], v[160:163], v[194:197], v[28:31]
	v_mfma_f32_16x16x32_bf16 v[20:23], v[168:171], v[194:197], v[20:23]
	v_mfma_f32_16x16x32_bf16 v[4:7], v[168:171], v[202:205], v[4:7]
	v_mfma_f32_16x16x32_bf16 v[12:15], v[160:163], v[202:205], v[12:15]
	v_mfma_f32_16x16x32_bf16 v[68:71], v[164:167], v[180:183], v[68:71]
	v_mfma_f32_16x16x32_bf16 v[52:55], v[172:175], v[180:183], v[52:55]
	v_mfma_f32_16x16x32_bf16 v[36:39], v[172:175], v[190:193], v[36:39]
	v_mfma_f32_16x16x32_bf16 v[44:47], v[164:167], v[190:193], v[44:47]
	v_mfma_f32_16x16x32_bf16 v[28:31], v[164:167], v[198:201], v[28:31]
	v_mfma_f32_16x16x32_bf16 v[20:23], v[172:175], v[198:201], v[20:23]
	v_mfma_f32_16x16x32_bf16 v[4:7], v[172:175], v[206:209], v[4:7]
	v_mfma_f32_16x16x32_bf16 v[12:15], v[164:167], v[206:209], v[12:15]
	s_setprio 0
	s_barrier
	ds_read_b128 v[132:135], v150
	ds_read_b128 v[136:139], v150 offset:1024
	ds_read_b128 v[152:155], v150 offset:2048
	ds_read_b128 v[156:159], v150 offset:3072
	ds_read_b128 v[160:163], v151
	ds_read_b128 v[164:167], v151 offset:1024
	ds_read_b128 v[168:171], v151 offset:2048
	ds_read_b128 v[172:175], v151 offset:3072
	ds_read_b128 v[176:179], v149 offset:32768
	ds_read_b128 v[180:183], v149 offset:33792
	ds_read_b128 v[186:189], v149 offset:34816
	ds_read_b128 v[190:193], v149 offset:35840
	ds_read_b128 v[194:197], v149 offset:36864
	ds_read_b128 v[198:201], v149 offset:37888
	ds_read_b128 v[202:205], v149 offset:38912
	ds_read_b128 v[206:209], v149 offset:39936
	s_add_u32 s28, s34, 0x40000
	s_addc_u32 s29, s35, 0
	s_mov_b32 s34, m0
	s_mov_b32 m0, s37
	s_nop 0
	global_load_lds_dwordx4 v142, s[28:29]
	s_mov_b32 m0, s34
	s_nop 0
	s_mov_b32 s34, m0
	s_mov_b32 m0, s38
	s_nop 0
	global_load_lds_dwordx4 v143, s[28:29]
	s_mov_b32 m0, s34
	s_waitcnt vmcnt(8)
	s_waitcnt lgkmcnt(0)
	s_barrier
	s_setprio 1
	s_waitcnt lgkmcnt(7)
	v_mfma_f32_16x16x32_bf16 v[120:123], v[132:135], v[176:179], v[120:123]
	v_mfma_f32_16x16x32_bf16 v[112:115], v[152:155], v[176:179], v[112:115]
	s_waitcnt lgkmcnt(5)
	v_mfma_f32_16x16x32_bf16 v[96:99], v[152:155], v[186:189], v[96:99]
	v_mfma_f32_16x16x32_bf16 v[104:107], v[132:135], v[186:189], v[104:107]
	s_waitcnt lgkmcnt(3)
	v_mfma_f32_16x16x32_bf16 v[88:91], v[132:135], v[194:197], v[88:91]
	v_mfma_f32_16x16x32_bf16 v[80:83], v[152:155], v[194:197], v[80:83]
	s_waitcnt lgkmcnt(1)
	v_mfma_f32_16x16x32_bf16 v[56:59], v[152:155], v[202:205], v[56:59]
	v_mfma_f32_16x16x32_bf16 v[72:75], v[132:135], v[202:205], v[72:75]
	v_mfma_f32_16x16x32_bf16 v[120:123], v[136:139], v[180:183], v[120:123]
	v_mfma_f32_16x16x32_bf16 v[112:115], v[156:159], v[180:183], v[112:115]
	v_mfma_f32_16x16x32_bf16 v[96:99], v[156:159], v[190:193], v[96:99]
	v_mfma_f32_16x16x32_bf16 v[104:107], v[136:139], v[190:193], v[104:107]
	v_mfma_f32_16x16x32_bf16 v[88:91], v[136:139], v[198:201], v[88:91]
	v_mfma_f32_16x16x32_bf16 v[80:83], v[156:159], v[198:201], v[80:83]
	s_waitcnt lgkmcnt(0)
	v_mfma_f32_16x16x32_bf16 v[56:59], v[156:159], v[206:209], v[56:59]
	v_mfma_f32_16x16x32_bf16 v[72:75], v[136:139], v[206:209], v[72:75]
	s_setprio 0
	s_setprio 1
	v_mfma_f32_16x16x32_bf16 v[124:127], v[160:163], v[176:179], v[124:127]
	v_mfma_f32_16x16x32_bf16 v[116:119], v[168:171], v[176:179], v[116:119]
	v_mfma_f32_16x16x32_bf16 v[100:103], v[168:171], v[186:189], v[100:103]
	v_mfma_f32_16x16x32_bf16 v[108:111], v[160:163], v[186:189], v[108:111]
	v_mfma_f32_16x16x32_bf16 v[92:95], v[160:163], v[194:197], v[92:95]
	v_mfma_f32_16x16x32_bf16 v[84:87], v[168:171], v[194:197], v[84:87]
	v_mfma_f32_16x16x32_bf16 v[64:67], v[168:171], v[202:205], v[64:67]
	v_mfma_f32_16x16x32_bf16 v[76:79], v[160:163], v[202:205], v[76:79]
	v_mfma_f32_16x16x32_bf16 v[124:127], v[164:167], v[180:183], v[124:127]
	v_mfma_f32_16x16x32_bf16 v[116:119], v[172:175], v[180:183], v[116:119]
	v_mfma_f32_16x16x32_bf16 v[100:103], v[172:175], v[190:193], v[100:103]
	v_mfma_f32_16x16x32_bf16 v[108:111], v[164:167], v[190:193], v[108:111]
	v_mfma_f32_16x16x32_bf16 v[92:95], v[164:167], v[198:201], v[92:95]
	v_mfma_f32_16x16x32_bf16 v[84:87], v[172:175], v[198:201], v[84:87]
	v_mfma_f32_16x16x32_bf16 v[64:67], v[172:175], v[206:209], v[64:67]
	v_mfma_f32_16x16x32_bf16 v[76:79], v[164:167], v[206:209], v[76:79]
	s_setprio 0
	s_barrier
	ds_read_b128 v[176:179], v149 offset:49152
	ds_read_b128 v[180:183], v149 offset:50176
	ds_read_b128 v[186:189], v149 offset:51200
	ds_read_b128 v[190:193], v149 offset:52224
	ds_read_b128 v[194:197], v149 offset:53248
	ds_read_b128 v[198:201], v149 offset:54272
	ds_read_b128 v[202:205], v149 offset:55296
	ds_read_b128 v[206:209], v149 offset:56320
	s_add_u32 s28, s30, 0x80
	s_addc_u32 s29, s31, 0
	s_mov_b32 s34, m0
	s_mov_b32 m0, s40
	s_nop 0
	global_load_lds_dwordx4 v140, s[28:29]
	s_mov_b32 m0, s34
	s_nop 0
	s_mov_b32 s34, m0
	s_mov_b32 m0, s41
	s_nop 0
	global_load_lds_dwordx4 v141, s[28:29]
	s_mov_b32 m0, s34
	s_add_u32 s28, s30, 0x40080
	s_addc_u32 s29, s31, 0
	s_mov_b32 s30, m0
	s_mov_b32 m0, s48
	s_nop 0
	global_load_lds_dwordx4 v140, s[28:29]
	s_mov_b32 m0, s30
	s_nop 0
	s_mov_b32 s30, m0
	s_mov_b32 m0, s49
	s_nop 0
	global_load_lds_dwordx4 v141, s[28:29]
	s_mov_b32 m0, s30
	s_mov_b32 s28, m0
	s_mov_b32 m0, s42
	s_nop 0
	global_load_lds_dwordx4 v142, s[26:27]
	s_mov_b32 m0, s28
	s_nop 0
	s_mov_b32 s28, m0
	s_mov_b32 m0, s43
	s_nop 0
	global_load_lds_dwordx4 v143, s[26:27]
	s_mov_b32 m0, s28
	s_waitcnt vmcnt(8)
	s_waitcnt lgkmcnt(0)
	s_barrier
	s_setprio 1
	s_waitcnt lgkmcnt(7)
	v_mfma_f32_16x16x32_bf16 v[60:63], v[132:135], v[176:179], v[60:63]
	v_mfma_f32_16x16x32_bf16 v[48:51], v[152:155], v[176:179], v[48:51]
	s_waitcnt lgkmcnt(5)
	v_mfma_f32_16x16x32_bf16 v[32:35], v[152:155], v[186:189], v[32:35]
	v_mfma_f32_16x16x32_bf16 v[40:43], v[132:135], v[186:189], v[40:43]
	s_waitcnt lgkmcnt(3)
	v_mfma_f32_16x16x32_bf16 v[24:27], v[132:135], v[194:197], v[24:27]
	v_mfma_f32_16x16x32_bf16 v[16:19], v[152:155], v[194:197], v[16:19]
	s_waitcnt lgkmcnt(1)
	v_mfma_f32_16x16x32_bf16 v[0:3], v[152:155], v[202:205], v[0:3]
	v_mfma_f32_16x16x32_bf16 v[8:11], v[132:135], v[202:205], v[8:11]
	v_mfma_f32_16x16x32_bf16 v[60:63], v[136:139], v[180:183], v[60:63]
	v_mfma_f32_16x16x32_bf16 v[48:51], v[156:159], v[180:183], v[48:51]
	v_mfma_f32_16x16x32_bf16 v[32:35], v[156:159], v[190:193], v[32:35]
	v_mfma_f32_16x16x32_bf16 v[40:43], v[136:139], v[190:193], v[40:43]
	v_mfma_f32_16x16x32_bf16 v[24:27], v[136:139], v[198:201], v[24:27]
	v_mfma_f32_16x16x32_bf16 v[16:19], v[156:159], v[198:201], v[16:19]
	s_waitcnt lgkmcnt(0)
	v_mfma_f32_16x16x32_bf16 v[0:3], v[156:159], v[206:209], v[0:3]
	v_mfma_f32_16x16x32_bf16 v[8:11], v[136:139], v[206:209], v[8:11]
	s_setprio 0
	s_setprio 1
	v_mfma_f32_16x16x32_bf16 v[68:71], v[160:163], v[176:179], v[68:71]
	v_mfma_f32_16x16x32_bf16 v[52:55], v[168:171], v[176:179], v[52:55]
	v_mfma_f32_16x16x32_bf16 v[36:39], v[168:171], v[186:189], v[36:39]
	v_mfma_f32_16x16x32_bf16 v[44:47], v[160:163], v[186:189], v[44:47]
	v_mfma_f32_16x16x32_bf16 v[28:31], v[160:163], v[194:197], v[28:31]
	v_mfma_f32_16x16x32_bf16 v[20:23], v[168:171], v[194:197], v[20:23]
	v_mfma_f32_16x16x32_bf16 v[4:7], v[168:171], v[202:205], v[4:7]
	v_mfma_f32_16x16x32_bf16 v[12:15], v[160:163], v[202:205], v[12:15]
	v_mfma_f32_16x16x32_bf16 v[68:71], v[164:167], v[180:183], v[68:71]
	v_mfma_f32_16x16x32_bf16 v[52:55], v[172:175], v[180:183], v[52:55]
	v_mfma_f32_16x16x32_bf16 v[36:39], v[172:175], v[190:193], v[36:39]
	v_mfma_f32_16x16x32_bf16 v[44:47], v[164:167], v[190:193], v[44:47]
	v_mfma_f32_16x16x32_bf16 v[28:31], v[164:167], v[198:201], v[28:31]
	v_mfma_f32_16x16x32_bf16 v[20:23], v[172:175], v[198:201], v[20:23]
	v_mfma_f32_16x16x32_bf16 v[4:7], v[172:175], v[206:209], v[4:7]
	v_mfma_f32_16x16x32_bf16 v[12:15], v[164:167], v[206:209], v[12:15]
	s_setprio 0
	s_barrier
	s_add_i32 s79, s79, 2
	s_add_u32 s77, s77, 0x100
	s_addc_u32 s78, s78, 0
	s_cmp_gt_u32 s79, 13
	s_mov_b64 s[28:29], s[24:25]
	s_cbranch_scc0 .LBB0_1254
	s_and_b64 vcc, exec, s[10:11]
	s_cbranch_vccz .LBB0_1257
	s_barrier

.LBB0_1373:
	ds_read_b128 v[112:115], v174
	ds_read_b128 v[132:135], v174 offset:1024
	ds_read_b128 v[136:139], v174 offset:2048
	ds_read_b128 v[140:143], v174 offset:3072
	ds_read_b128 v[144:147], v175
	ds_read_b128 v[148:151], v175 offset:1024
	ds_read_b128 v[152:155], v175 offset:2048
	ds_read_b128 v[156:159], v175 offset:3072
	s_add_u32 s12, s16, 0x100
	s_addc_u32 s13, s17, 0
	s_cmp_eq_u32 s58, 40
	s_cselect_b32 s20, s8, s12
	s_cselect_b32 s21, s9, s13
	s_cselect_b32 s18, s10, s55
	s_cselect_b32 s19, s11, s57
	s_add_u32 s14, s20, 0x80
	s_addc_u32 s15, s21, 0
	ds_read_b128 v[160:163], v176
	ds_read_b128 v[180:183], v176 offset:1024
	ds_read_b128 v[184:187], v176 offset:2048
	ds_read_b128 v[188:191], v176 offset:3072
	ds_read_b128 v[192:195], v176 offset:4096
	ds_read_b128 v[196:199], v176 offset:5120
	ds_read_b128 v[200:203], v176 offset:6144
	ds_read_b128 v[204:207], v176 offset:7168
	s_add_u32 s16, s16, 0xb0080
	s_addc_u32 s17, s17, 0
	s_mov_b32 s59, m0
	s_mov_b32 m0, s34
	s_nop 0
	global_load_lds_dwordx4 v170, s[16:17]
	s_mov_b32 m0, s59
	s_nop 0
	s_mov_b32 s59, m0
	s_mov_b32 m0, s38
	s_nop 0
	global_load_lds_dwordx4 v171, s[16:17]
	s_mov_b32 m0, s59
	s_waitcnt vmcnt(8)
	s_waitcnt lgkmcnt(0)
	s_barrier
	s_setprio 1
	s_waitcnt lgkmcnt(7)
	v_mfma_f32_16x16x32_bf16 v[120:123], v[112:115], v[160:163], v[120:123]
	v_mfma_f32_16x16x32_bf16 v[116:119], v[136:139], v[160:163], v[116:119]
	s_waitcnt lgkmcnt(5)
	v_mfma_f32_16x16x32_bf16 v[104:107], v[136:139], v[184:187], v[104:107]
	v_mfma_f32_16x16x32_bf16 v[108:111], v[112:115], v[184:187], v[108:111]
	s_waitcnt lgkmcnt(3)
	v_mfma_f32_16x16x32_bf16 v[92:95], v[112:115], v[192:195], v[92:95]
	v_mfma_f32_16x16x32_bf16 v[88:91], v[136:139], v[192:195], v[88:91]
	s_waitcnt lgkmcnt(1)
	v_mfma_f32_16x16x32_bf16 v[72:75], v[136:139], v[200:203], v[72:75]
	v_mfma_f32_16x16x32_bf16 v[76:79], v[112:115], v[200:203], v[76:79]
	v_mfma_f32_16x16x32_bf16 v[120:123], v[132:135], v[180:183], v[120:123]
	v_mfma_f32_16x16x32_bf16 v[116:119], v[140:143], v[180:183], v[116:119]
	v_mfma_f32_16x16x32_bf16 v[104:107], v[140:143], v[188:191], v[104:107]
	v_mfma_f32_16x16x32_bf16 v[108:111], v[132:135], v[188:191], v[108:111]
	v_mfma_f32_16x16x32_bf16 v[92:95], v[132:135], v[196:199], v[92:95]
	v_mfma_f32_16x16x32_bf16 v[88:91], v[140:143], v[196:199], v[88:91]
	s_waitcnt lgkmcnt(0)
	v_mfma_f32_16x16x32_bf16 v[72:75], v[140:143], v[204:207], v[72:75]
	v_mfma_f32_16x16x32_bf16 v[76:79], v[132:135], v[204:207], v[76:79]
	s_setprio 0
	s_setprio 1
	v_mfma_f32_16x16x32_bf16 v[128:131], v[144:147], v[160:163], v[128:131]
	v_mfma_f32_16x16x32_bf16 v[124:127], v[152:155], v[160:163], v[124:127]
	v_mfma_f32_16x16x32_bf16 v[96:99], v[152:155], v[184:187], v[96:99]
	v_mfma_f32_16x16x32_bf16 v[100:103], v[144:147], v[184:187], v[100:103]
	v_mfma_f32_16x16x32_bf16 v[84:87], v[144:147], v[192:195], v[84:87]
	v_mfma_f32_16x16x32_bf16 v[80:83], v[152:155], v[192:195], v[80:83]
	v_mfma_f32_16x16x32_bf16 v[56:59], v[152:155], v[200:203], v[56:59]
	v_mfma_f32_16x16x32_bf16 v[60:63], v[144:147], v[200:203], v[60:63]
	v_mfma_f32_16x16x32_bf16 v[128:131], v[148:151], v[180:183], v[128:131]
	v_mfma_f32_16x16x32_bf16 v[124:127], v[156:159], v[180:183], v[124:127]
	v_mfma_f32_16x16x32_bf16 v[96:99], v[156:159], v[188:191], v[96:99]
	v_mfma_f32_16x16x32_bf16 v[100:103], v[148:151], v[188:191], v[100:103]
	v_mfma_f32_16x16x32_bf16 v[84:87], v[148:151], v[196:199], v[84:87]
	v_mfma_f32_16x16x32_bf16 v[80:83], v[156:159], v[196:199], v[80:83]
	v_mfma_f32_16x16x32_bf16 v[56:59], v[156:159], v[204:207], v[56:59]
	v_mfma_f32_16x16x32_bf16 v[60:63], v[148:151], v[204:207], v[60:63]
	s_setprio 0
	s_barrier
	ds_read_b128 v[160:163], v176 offset:16384
	ds_read_b128 v[180:183], v176 offset:17408
	ds_read_b128 v[184:187], v176 offset:18432
	ds_read_b128 v[188:191], v176 offset:19456
	ds_read_b128 v[192:195], v176 offset:20480
	ds_read_b128 v[196:199], v176 offset:21504
	ds_read_b128 v[200:203], v176 offset:22528
	ds_read_b128 v[204:207], v176 offset:23552
	s_mov_b32 s16, m0
	s_mov_b32 m0, s36
	s_nop 0
	global_load_lds_dwordx4 v168, s[18:19]
	s_mov_b32 m0, s16
	s_nop 0
	s_mov_b32 s16, m0
	s_mov_b32 m0, s39
	s_nop 0
	global_load_lds_dwordx4 v169, s[18:19]
	s_mov_b32 m0, s16
	s_add_u32 s16, s18, 0xb0000
	s_addc_u32 s17, s19, 0
	s_mov_b32 s59, m0
	s_mov_b32 m0, s37
	s_nop 0
	global_load_lds_dwordx4 v168, s[16:17]
	s_mov_b32 m0, s59
	s_nop 0
	s_mov_b32 s59, m0
	s_mov_b32 m0, s40
	s_nop 0
	global_load_lds_dwordx4 v169, s[16:17]
	s_mov_b32 m0, s59
	s_mov_b32 s16, m0
	s_mov_b32 m0, s22
	s_nop 0
	global_load_lds_dwordx4 v170, s[20:21]
	s_mov_b32 m0, s16
	s_nop 0
	s_mov_b32 s16, m0
	s_mov_b32 m0, s23
	s_nop 0
	global_load_lds_dwordx4 v171, s[20:21]
	s_mov_b32 m0, s16
	s_waitcnt vmcnt(8)
	s_waitcnt lgkmcnt(0)
	s_barrier
	s_setprio 1
	s_waitcnt lgkmcnt(7)
	v_mfma_f32_16x16x32_bf16 v[68:71], v[112:115], v[160:163], v[68:71]
	v_mfma_f32_16x16x32_bf16 v[64:67], v[136:139], v[160:163], v[64:67]
	s_waitcnt lgkmcnt(5)
	v_mfma_f32_16x16x32_bf16 v[40:43], v[136:139], v[184:187], v[40:43]
	v_mfma_f32_16x16x32_bf16 v[44:47], v[112:115], v[184:187], v[44:47]
	s_waitcnt lgkmcnt(3)
	v_mfma_f32_16x16x32_bf16 v[28:31], v[112:115], v[192:195], v[28:31]
	v_mfma_f32_16x16x32_bf16 v[24:27], v[136:139], v[192:195], v[24:27]
	s_waitcnt lgkmcnt(1)
	v_mfma_f32_16x16x32_bf16 v[8:11], v[136:139], v[200:203], v[8:11]
	v_mfma_f32_16x16x32_bf16 v[12:15], v[112:115], v[200:203], v[12:15]
	v_mfma_f32_16x16x32_bf16 v[68:71], v[132:135], v[180:183], v[68:71]
	v_mfma_f32_16x16x32_bf16 v[64:67], v[140:143], v[180:183], v[64:67]
	v_mfma_f32_16x16x32_bf16 v[40:43], v[140:143], v[188:191], v[40:43]
	v_mfma_f32_16x16x32_bf16 v[44:47], v[132:135], v[188:191], v[44:47]
	v_mfma_f32_16x16x32_bf16 v[28:31], v[132:135], v[196:199], v[28:31]
	v_mfma_f32_16x16x32_bf16 v[24:27], v[140:143], v[196:199], v[24:27]
	s_waitcnt lgkmcnt(0)
	v_mfma_f32_16x16x32_bf16 v[8:11], v[140:143], v[204:207], v[8:11]
	v_mfma_f32_16x16x32_bf16 v[12:15], v[132:135], v[204:207], v[12:15]
	s_setprio 0
	s_setprio 1
	v_mfma_f32_16x16x32_bf16 v[52:55], v[144:147], v[160:163], v[52:55]
	v_mfma_f32_16x16x32_bf16 v[48:51], v[152:155], v[160:163], v[48:51]
	v_mfma_f32_16x16x32_bf16 v[32:35], v[152:155], v[184:187], v[32:35]
	v_mfma_f32_16x16x32_bf16 v[36:39], v[144:147], v[184:187], v[36:39]
	v_mfma_f32_16x16x32_bf16 v[20:23], v[144:147], v[192:195], v[20:23]
	v_mfma_f32_16x16x32_bf16 v[16:19], v[152:155], v[192:195], v[16:19]
	v_mfma_f32_16x16x32_bf16 v[0:3], v[152:155], v[200:203], v[0:3]
	v_mfma_f32_16x16x32_bf16 v[4:7], v[144:147], v[200:203], v[4:7]
	v_mfma_f32_16x16x32_bf16 v[52:55], v[148:151], v[180:183], v[52:55]
	v_mfma_f32_16x16x32_bf16 v[48:51], v[156:159], v[180:183], v[48:51]
	v_mfma_f32_16x16x32_bf16 v[32:35], v[156:159], v[188:191], v[32:35]
	v_mfma_f32_16x16x32_bf16 v[36:39], v[148:151], v[188:191], v[36:39]
	v_mfma_f32_16x16x32_bf16 v[20:23], v[148:151], v[196:199], v[20:23]
	v_mfma_f32_16x16x32_bf16 v[16:19], v[156:159], v[196:199], v[16:19]
	v_mfma_f32_16x16x32_bf16 v[0:3], v[156:159], v[204:207], v[0:3]
	v_mfma_f32_16x16x32_bf16 v[4:7], v[148:151], v[204:207], v[4:7]
	s_setprio 0
	s_barrier
	ds_read_b128 v[112:115], v177
	ds_read_b128 v[132:135], v177 offset:1024
	ds_read_b128 v[136:139], v177 offset:2048
	ds_read_b128 v[140:143], v177 offset:3072
	ds_read_b128 v[144:147], v178
	ds_read_b128 v[148:151], v178 offset:1024
	ds_read_b128 v[152:155], v178 offset:2048
	ds_read_b128 v[156:159], v178 offset:3072
	ds_read_b128 v[160:163], v176 offset:32768
	ds_read_b128 v[180:183], v176 offset:33792
	ds_read_b128 v[184:187], v176 offset:34816
	ds_read_b128 v[188:191], v176 offset:35840
	ds_read_b128 v[192:195], v176 offset:36864
	ds_read_b128 v[196:199], v176 offset:37888
	ds_read_b128 v[200:203], v176 offset:38912
	ds_read_b128 v[204:207], v176 offset:39936
	s_add_u32 s16, s20, 0xb0000
	s_addc_u32 s17, s21, 0
	s_mov_b32 s20, m0
	s_mov_b32 m0, s24
	s_nop 0
	global_load_lds_dwordx4 v170, s[16:17]
	s_mov_b32 m0, s20
	s_nop 0
	s_mov_b32 s20, m0
	s_mov_b32 m0, s25
	s_nop 0
	global_load_lds_dwordx4 v171, s[16:17]
	s_mov_b32 m0, s20
	s_waitcnt vmcnt(8)
	s_waitcnt lgkmcnt(0)
	s_barrier
	s_setprio 1
	s_waitcnt lgkmcnt(7)
	v_mfma_f32_16x16x32_bf16 v[120:123], v[112:115], v[160:163], v[120:123]
	v_mfma_f32_16x16x32_bf16 v[116:119], v[136:139], v[160:163], v[116:119]
	s_waitcnt lgkmcnt(5)
	v_mfma_f32_16x16x32_bf16 v[104:107], v[136:139], v[184:187], v[104:107]
	v_mfma_f32_16x16x32_bf16 v[108:111], v[112:115], v[184:187], v[108:111]
	s_waitcnt lgkmcnt(3)
	v_mfma_f32_16x16x32_bf16 v[92:95], v[112:115], v[192:195], v[92:95]
	v_mfma_f32_16x16x32_bf16 v[88:91], v[136:139], v[192:195], v[88:91]
	s_waitcnt lgkmcnt(1)
	v_mfma_f32_16x16x32_bf16 v[72:75], v[136:139], v[200:203], v[72:75]
	v_mfma_f32_16x16x32_bf16 v[76:79], v[112:115], v[200:203], v[76:79]
	v_mfma_f32_16x16x32_bf16 v[120:123], v[132:135], v[180:183], v[120:123]
	v_mfma_f32_16x16x32_bf16 v[116:119], v[140:143], v[180:183], v[116:119]
	v_mfma_f32_16x16x32_bf16 v[104:107], v[140:143], v[188:191], v[104:107]
	v_mfma_f32_16x16x32_bf16 v[108:111], v[132:135], v[188:191], v[108:111]
	v_mfma_f32_16x16x32_bf16 v[92:95], v[132:135], v[196:199], v[92:95]
	v_mfma_f32_16x16x32_bf16 v[88:91], v[140:143], v[196:199], v[88:91]
	s_waitcnt lgkmcnt(0)
	v_mfma_f32_16x16x32_bf16 v[72:75], v[140:143], v[204:207], v[72:75]
	v_mfma_f32_16x16x32_bf16 v[76:79], v[132:135], v[204:207], v[76:79]
	s_setprio 0
	s_setprio 1
	v_mfma_f32_16x16x32_bf16 v[128:131], v[144:147], v[160:163], v[128:131]
	v_mfma_f32_16x16x32_bf16 v[124:127], v[152:155], v[160:163], v[124:127]
	v_mfma_f32_16x16x32_bf16 v[96:99], v[152:155], v[184:187], v[96:99]
	v_mfma_f32_16x16x32_bf16 v[100:103], v[144:147], v[184:187], v[100:103]
	v_mfma_f32_16x16x32_bf16 v[84:87], v[144:147], v[192:195], v[84:87]
	v_mfma_f32_16x16x32_bf16 v[80:83], v[152:155], v[192:195], v[80:83]
	v_mfma_f32_16x16x32_bf16 v[56:59], v[152:155], v[200:203], v[56:59]
	v_mfma_f32_16x16x32_bf16 v[60:63], v[144:147], v[200:203], v[60:63]
	v_mfma_f32_16x16x32_bf16 v[128:131], v[148:151], v[180:183], v[128:131]
	v_mfma_f32_16x16x32_bf16 v[124:127], v[156:159], v[180:183], v[124:127]
	v_mfma_f32_16x16x32_bf16 v[96:99], v[156:159], v[188:191], v[96:99]
	v_mfma_f32_16x16x32_bf16 v[100:103], v[148:151], v[188:191], v[100:103]
	v_mfma_f32_16x16x32_bf16 v[84:87], v[148:151], v[196:199], v[84:87]
	v_mfma_f32_16x16x32_bf16 v[80:83], v[156:159], v[196:199], v[80:83]
	v_mfma_f32_16x16x32_bf16 v[56:59], v[156:159], v[204:207], v[56:59]
	v_mfma_f32_16x16x32_bf16 v[60:63], v[148:151], v[204:207], v[60:63]
	s_setprio 0
	s_barrier
	ds_read_b128 v[160:163], v176 offset:49152
	ds_read_b128 v[180:183], v176 offset:50176
	ds_read_b128 v[184:187], v176 offset:51200
	ds_read_b128 v[188:191], v176 offset:52224
	ds_read_b128 v[192:195], v176 offset:53248
	ds_read_b128 v[196:199], v176 offset:54272
	ds_read_b128 v[200:203], v176 offset:55296
	ds_read_b128 v[204:207], v176 offset:56320
	s_add_u32 s16, s18, 0x80
	s_addc_u32 s17, s19, 0
	s_mov_b32 s20, m0
	s_mov_b32 m0, s27
	s_nop 0
	global_load_lds_dwordx4 v168, s[16:17]
	s_mov_b32 m0, s20
	s_nop 0
	s_mov_b32 s20, m0
	s_mov_b32 m0, s28
	s_nop 0
	global_load_lds_dwordx4 v169, s[16:17]
	s_mov_b32 m0, s20
	s_add_u32 s16, s18, 0xb0080
	s_addc_u32 s17, s19, 0
	s_mov_b32 s18, m0
	s_mov_b32 m0, s31
	s_nop 0
	global_load_lds_dwordx4 v168, s[16:17]
	s_mov_b32 m0, s18
	s_nop 0
	s_mov_b32 s18, m0
	s_mov_b32 m0, s33
	s_nop 0
	global_load_lds_dwordx4 v169, s[16:17]
	s_mov_b32 m0, s18
	s_mov_b32 s16, m0
	s_mov_b32 m0, s29
	s_nop 0
	global_load_lds_dwordx4 v170, s[14:15]
	s_mov_b32 m0, s16
	s_nop 0
	s_mov_b32 s16, m0
	s_mov_b32 m0, s30
	s_nop 0
	global_load_lds_dwordx4 v171, s[14:15]
	s_mov_b32 m0, s16
	s_waitcnt vmcnt(8)
	s_waitcnt lgkmcnt(0)
	s_barrier
	s_setprio 1
	s_waitcnt lgkmcnt(7)
	v_mfma_f32_16x16x32_bf16 v[68:71], v[112:115], v[160:163], v[68:71]
	v_mfma_f32_16x16x32_bf16 v[64:67], v[136:139], v[160:163], v[64:67]
	s_waitcnt lgkmcnt(5)
	v_mfma_f32_16x16x32_bf16 v[40:43], v[136:139], v[184:187], v[40:43]
	v_mfma_f32_16x16x32_bf16 v[44:47], v[112:115], v[184:187], v[44:47]
	s_waitcnt lgkmcnt(3)
	v_mfma_f32_16x16x32_bf16 v[28:31], v[112:115], v[192:195], v[28:31]
	v_mfma_f32_16x16x32_bf16 v[24:27], v[136:139], v[192:195], v[24:27]
	s_waitcnt lgkmcnt(1)
	v_mfma_f32_16x16x32_bf16 v[8:11], v[136:139], v[200:203], v[8:11]
	v_mfma_f32_16x16x32_bf16 v[12:15], v[112:115], v[200:203], v[12:15]
	v_mfma_f32_16x16x32_bf16 v[68:71], v[132:135], v[180:183], v[68:71]
	v_mfma_f32_16x16x32_bf16 v[64:67], v[140:143], v[180:183], v[64:67]
	v_mfma_f32_16x16x32_bf16 v[40:43], v[140:143], v[188:191], v[40:43]
	v_mfma_f32_16x16x32_bf16 v[44:47], v[132:135], v[188:191], v[44:47]
	v_mfma_f32_16x16x32_bf16 v[28:31], v[132:135], v[196:199], v[28:31]
	v_mfma_f32_16x16x32_bf16 v[24:27], v[140:143], v[196:199], v[24:27]
	s_waitcnt lgkmcnt(0)
	v_mfma_f32_16x16x32_bf16 v[8:11], v[140:143], v[204:207], v[8:11]
	v_mfma_f32_16x16x32_bf16 v[12:15], v[132:135], v[204:207], v[12:15]
	s_setprio 0
	s_setprio 1
	v_mfma_f32_16x16x32_bf16 v[52:55], v[144:147], v[160:163], v[52:55]
	v_mfma_f32_16x16x32_bf16 v[48:51], v[152:155], v[160:163], v[48:51]
	v_mfma_f32_16x16x32_bf16 v[32:35], v[152:155], v[184:187], v[32:35]
	v_mfma_f32_16x16x32_bf16 v[36:39], v[144:147], v[184:187], v[36:39]
	v_mfma_f32_16x16x32_bf16 v[20:23], v[144:147], v[192:195], v[20:23]
	v_mfma_f32_16x16x32_bf16 v[16:19], v[152:155], v[192:195], v[16:19]
	v_mfma_f32_16x16x32_bf16 v[0:3], v[152:155], v[200:203], v[0:3]
	v_mfma_f32_16x16x32_bf16 v[4:7], v[144:147], v[200:203], v[4:7]
	v_mfma_f32_16x16x32_bf16 v[52:55], v[148:151], v[180:183], v[52:55]
	v_mfma_f32_16x16x32_bf16 v[48:51], v[156:159], v[180:183], v[48:51]
	v_mfma_f32_16x16x32_bf16 v[32:35], v[156:159], v[188:191], v[32:35]
	v_mfma_f32_16x16x32_bf16 v[36:39], v[148:151], v[188:191], v[36:39]
	v_mfma_f32_16x16x32_bf16 v[20:23], v[148:151], v[196:199], v[20:23]
	v_mfma_f32_16x16x32_bf16 v[16:19], v[156:159], v[196:199], v[16:19]
	v_mfma_f32_16x16x32_bf16 v[0:3], v[156:159], v[204:207], v[0:3]
	v_mfma_f32_16x16x32_bf16 v[4:7], v[148:151], v[204:207], v[4:7]
	s_setprio 0
	s_barrier
	s_add_i32 s58, s58, 2
	s_add_u32 s55, s55, 0x100
	s_addc_u32 s57, s57, 0
	s_cmp_gt_u32 s58, 41
	s_mov_b64 s[16:17], s[12:13]
	s_cbranch_scc0 .LBB0_1373
	s_and_b64 vcc, exec, s[6:7]
	s_cbranch_vccz .LBB0_1376
	s_barrier
